# best + first K-iteration peeled with srcC=0 MFMAs, accumulator zeroing (128 VGPR writes per unit) removed
# speedup vs baseline: 1.0193x; 1.0023x over previous
; #define PG8_STAGE(bufoff, gbase, voff) do { _Pragma("unroll") for (int _i = 0; _i < 2; ++_i) \
;         __builtin_amdgcn_global_load_lds((const unsigned*)((const char*)(gbase) + (voff)[_i]), (PG8_LAS unsigned*)(lds + (bufoff) + ldsw + _i * 8192), 16, 0, 0); } while (0)
; #define PG8_LDA(dst, b, h) do { _Pragma("unroll") for (int m = 0; m < 4; ++m) _Pragma("unroll") for (int k = 0; k < 2; ++k) dst[m][k] = *(const PG8_LAS bf16x8*)(lds + PG8_SA(b, h) + aoff + m * 2048 + k * 1024); } while (0)
; #define PG8_LDB(dst, b, h) do { _Pragma("unroll") for (int n = 0; n < 2; ++n) _Pragma("unroll") for (int k = 0; k < 2; ++k) dst[n][k] = *(const PG8_LAS bf16x8*)(lds + PG8_SB(b, h) + boff + n * 2048 + k * 1024); } while (0)
; #define PG8_MMA(ai, bj, At, Bt) do { __builtin_amdgcn_s_setprio(1); _Pragma("unroll") for (int m = 0; m < 4; ++m) _Pragma("unroll") for (int n = 0; n < 2; ++n) _Pragma("unroll") for (int k = 0; k < 2; ++k) \
;         acc[ai][bj][m][n] = __builtin_amdgcn_mfma_f32_16x16x32_bf16(Bt[n][k], At[m][k], acc[ai][bj][m][n], 0, 0, 0); __builtin_amdgcn_s_setprio(0); } while (0)
; #define PG8_WAIT_V(n) asm volatile("s_waitcnt vmcnt(" #n ")" ::: "memory")
; template <class Epi, class Sched, bool ALIGN_EPI = false, bool SP2 = false>
; __device__ __forceinline__ void gemm_phase(PG8_LAS unsigned char* lds, const Gemm g, const Sched& S, const Epi& E) {
;     ...
;         const char* nA = has_next ? (const char*)g.A + (size_t)nxt.pm * tstep : cA; const char* nB = has_next ? (const char*)g.Bt + (size_t)nxt.pn * tstep : cB;
;         for (int t = 0; t < nt; t += 2) {
;             const bool last = (t == nt - 2);
;             const char* a1 = cA + (size_t)(t + 1) * kstepA;
;             const char* a2 = last ? nA : cA + (size_t)(t + 2) * kstepA; const char* b2 = last ? nB : cB + (size_t)(t + 2) * kstep;
;             const char* a3 = a2 + kstepA; const char* b3 = b2 + kstep;
;             if (last && has_next) S.a_ready(nxt);
;             if constexpr (SP2) {
;             PG8_LDB(B0, 0, 0); PG8_LDB(B1, 0, 1); PG8_SCHED; PG8_LDA(At, 0, 0); PG8_STAGE(PG8_SA(1, 1), a1 + hstep, voffA);
;             PG8_WAIT_V(8); PG8_WAIT_L(0); PG8_BAR; PG8_MMA(0, 0, At, B0); PG8_MMA(0, 1, At, B1); PG8_BAR; PG8_SCHED;
;             PG8_LDA(At, 0, 1); PG8_STAGE(PG8_SB(0, 0), b2, voffB); PG8_STAGE(PG8_SB(0, 1), b2 + hstep, voffB); PG8_STAGE(PG8_SA(0, 0), a2, voffA);
.LBB0_237:
	s_ashr_i32 s11, s10, 31
	s_lshl_b64 s[2:3], s[10:11], 19
	s_add_u32 s12, s52, s2
	s_addc_u32 s13, s53, s3
	s_and_b64 s[2:3], s[40:41], exec
	s_cselect_b32 s11, s13, s25
	s_cselect_b32 s67, s12, s24
	s_ashr_i32 s9, s8, 31
	s_lshl_b64 s[2:3], s[8:9], 19
	s_add_u32 s44, s54, s2
	s_addc_u32 s45, s55, s3
	s_and_b64 s[2:3], s[40:41], exec
	s_cselect_b32 s9, s45, s27
	s_cselect_b32 s68, s44, s26
	s_add_u32 s69, s26, 0x100
	s_addc_u32 s70, s27, 0
	s_mov_b32 s71, -2
	s_add_u32 s2, s24, 0x8000
	s_addc_u32 s3, s25, 0
	s_cmp_eq_u32 s71, 12
	s_cselect_b32 s46, s67, s2
	s_cselect_b32 s47, s11, s3
	s_cselect_b32 s42, s68, s69
	s_cselect_b32 s43, s9, s70
	s_add_u32 s26, s46, 0x4000
	s_addc_u32 s27, s47, 0
	v_add_u32_e32 v148, s76, v150
	s_add_i32 s72, 0, 0x14000
	ds_read_b128 v[144:147], v148
	ds_read_b128 v[160:163], v148 offset:1024
	ds_read_b128 v[164:167], v148 offset:2048
	ds_read_b128 v[168:171], v148 offset:3072
	v_add_u32_e32 v148, s72, v150
	ds_read_b128 v[172:175], v148
	ds_read_b128 v[176:179], v148 offset:1024
	ds_read_b128 v[180:183], v148 offset:2048
	ds_read_b128 v[184:187], v148 offset:3072
	v_lshl_add_u64 v[148:149], s[24:25], 0, v[142:143]
	s_add_i32 m0, s23, 0xc000
	ds_read_b128 v[188:191], v152
	ds_read_b128 v[206:209], v152 offset:1024
	ds_read_b128 v[210:213], v152 offset:2048
	ds_read_b128 v[214:217], v152 offset:3072
	ds_read_b128 v[218:221], v152 offset:4096
	ds_read_b128 v[222:225], v152 offset:5120
	ds_read_b128 v[226:229], v152 offset:6144
	ds_read_b128 v[230:233], v152 offset:7168
	global_load_lds_dwordx4 v[148:149], off
	v_lshl_add_u64 v[148:149], s[24:25], 0, v[140:141]
	s_add_i32 m0, s23, 0xe000
	s_nop 0
	global_load_lds_dwordx4 v[148:149], off
	s_waitcnt vmcnt(8)
	s_waitcnt lgkmcnt(0)
	s_barrier
	v_mfma_f32_16x16x32_bf16 v[126:129], v[144:147], v[188:191], 0
	v_mfma_f32_16x16x32_bf16 v[126:129], v[160:163], v[206:209], v[126:129]
	v_mfma_f32_16x16x32_bf16 v[122:125], v[168:171], v[206:209], 0
	v_mfma_f32_16x16x32_bf16 v[122:125], v[164:167], v[188:191], v[122:125]
	v_mfma_f32_16x16x32_bf16 v[106:109], v[164:167], v[210:213], 0
	v_mfma_f32_16x16x32_bf16 v[106:109], v[168:171], v[214:217], v[106:109]
	v_mfma_f32_16x16x32_bf16 v[110:113], v[160:163], v[214:217], 0
	v_mfma_f32_16x16x32_bf16 v[110:113], v[144:147], v[210:213], v[110:113]
	v_mfma_f32_16x16x32_bf16 v[94:97], v[144:147], v[218:221], 0
	v_mfma_f32_16x16x32_bf16 v[94:97], v[160:163], v[222:225], v[94:97]
	v_mfma_f32_16x16x32_bf16 v[90:93], v[168:171], v[222:225], 0
	v_mfma_f32_16x16x32_bf16 v[90:93], v[164:167], v[218:221], v[90:93]
	v_mfma_f32_16x16x32_bf16 v[74:77], v[164:167], v[226:229], 0
	v_mfma_f32_16x16x32_bf16 v[74:77], v[168:171], v[230:233], v[74:77]
	v_mfma_f32_16x16x32_bf16 v[78:81], v[160:163], v[230:233], 0
	v_mfma_f32_16x16x32_bf16 v[78:81], v[144:147], v[226:229], v[78:81]
	v_mfma_f32_16x16x32_bf16 v[118:121], v[172:175], v[188:191], 0
	v_mfma_f32_16x16x32_bf16 v[118:121], v[176:179], v[206:209], v[118:121]
	v_mfma_f32_16x16x32_bf16 v[114:117], v[184:187], v[206:209], 0
	v_mfma_f32_16x16x32_bf16 v[114:117], v[180:183], v[188:191], v[114:117]
	v_mfma_f32_16x16x32_bf16 v[98:101], v[180:183], v[210:213], 0
	v_mfma_f32_16x16x32_bf16 v[98:101], v[184:187], v[214:217], v[98:101]
	v_mfma_f32_16x16x32_bf16 v[102:105], v[176:179], v[214:217], 0
	v_mfma_f32_16x16x32_bf16 v[102:105], v[172:175], v[210:213], v[102:105]
	v_mfma_f32_16x16x32_bf16 v[86:89], v[172:175], v[218:221], 0
	v_mfma_f32_16x16x32_bf16 v[86:89], v[176:179], v[222:225], v[86:89]
	v_mfma_f32_16x16x32_bf16 v[82:85], v[184:187], v[222:225], 0
	v_mfma_f32_16x16x32_bf16 v[82:85], v[180:183], v[218:221], v[82:85]
	v_mfma_f32_16x16x32_bf16 v[66:69], v[180:183], v[226:229], 0
	v_mfma_f32_16x16x32_bf16 v[66:69], v[184:187], v[230:233], v[66:69]
	v_mfma_f32_16x16x32_bf16 v[70:73], v[176:179], v[230:233], 0
	v_mfma_f32_16x16x32_bf16 v[70:73], v[172:175], v[226:229], v[70:73]
	s_barrier
	s_add_i32 s24, s76, s51
	v_lshl_add_u64 v[148:149], s[42:43], 0, v[132:133]
	s_mov_b32 m0, s24
	ds_read_b128 v[188:191], v152 offset:16384
	ds_read_b128 v[206:209], v152 offset:17408
	ds_read_b128 v[210:213], v152 offset:18432
	ds_read_b128 v[214:217], v152 offset:19456
	ds_read_b128 v[218:221], v152 offset:20480
	ds_read_b128 v[222:225], v152 offset:21504
	ds_read_b128 v[226:229], v152 offset:22528
	ds_read_b128 v[230:233], v152 offset:23552
	global_load_lds_dwordx4 v[148:149], off
	s_add_i32 m0, s24, 0x2000
	s_add_u32 s24, s42, 0x40000
	v_lshl_add_u64 v[234:235], s[42:43], 0, v[136:137]
	s_addc_u32 s25, s43, 0
	s_add_i32 s72, s72, s51
	global_load_lds_dwordx4 v[234:235], off
	v_lshl_add_u64 v[236:237], s[24:25], 0, v[132:133]
	s_mov_b32 m0, s72
	s_nop 0
	global_load_lds_dwordx4 v[236:237], off
	v_lshl_add_u64 v[236:237], s[24:25], 0, v[136:137]
	s_add_i32 m0, s72, 0x2000
	s_nop 0
	global_load_lds_dwordx4 v[236:237], off
	v_lshl_add_u64 v[236:237], s[46:47], 0, v[130:131]
	s_mov_b32 m0, s23
	s_nop 0
	global_load_lds_dwordx4 v[236:237], off
	v_lshl_add_u64 v[236:237], s[46:47], 0, v[134:135]
	s_mov_b32 m0, s56
	s_nop 0
	global_load_lds_dwordx4 v[236:237], off
	s_waitcnt vmcnt(8)
	s_waitcnt lgkmcnt(0)
	s_barrier
; #define PG8_STAGE(bufoff, gbase, voff) do { _Pragma("unroll") for (int _i = 0; _i < 2; ++_i) \
;         __builtin_amdgcn_global_load_lds((const unsigned*)((const char*)(gbase) + (voff)[_i]), (PG8_LAS unsigned*)(lds + (bufoff) + ldsw + _i * 8192), 16, 0, 0); } while (0)
; #define PG8_LDA(dst, b, h) do { _Pragma("unroll") for (int m = 0; m < 4; ++m) _Pragma("unroll") for (int k = 0; k < 2; ++k) dst[m][k] = *(const PG8_LAS bf16x8*)(lds + PG8_SA(b, h) + aoff + m * 2048 + k * 1024); } while (0)
; #define PG8_LDB(dst, b, h) do { _Pragma("unroll") for (int n = 0; n < 2; ++n) _Pragma("unroll") for (int k = 0; k < 2; ++k) dst[n][k] = *(const PG8_LAS bf16x8*)(lds + PG8_SB(b, h) + boff + n * 2048 + k * 1024); } while (0)
; #define PG8_MMA(ai, bj, At, Bt) do { __builtin_amdgcn_s_setprio(1); _Pragma("unroll") for (int m = 0; m < 4; ++m) _Pragma("unroll") for (int n = 0; n < 2; ++n) _Pragma("unroll") for (int k = 0; k < 2; ++k) \
;         acc[ai][bj][m][n] = __builtin_amdgcn_mfma_f32_16x16x32_bf16(Bt[n][k], At[m][k], acc[ai][bj][m][n], 0, 0, 0); __builtin_amdgcn_s_setprio(0); } while (0)
; #define PG8_WAIT_V(n) asm volatile("s_waitcnt vmcnt(" #n ")" ::: "memory")
; #define PG8_WAIT_L(n) asm volatile("s_waitcnt lgkmcnt(" #n ")" ::: "memory")
; #define PG8_BAR __builtin_amdgcn_s_barrier()
; #define PG8_SCHED __builtin_amdgcn_sched_barrier(0)
; template <class Epi, class Sched, bool ALIGN_EPI = false, bool SP2 = false>
; __device__ __forceinline__ void gemm_phase(PG8_LAS unsigned char* lds, const Gemm g, const Sched& S, const Epi& E) {
;     ...
;             PG8_WAIT_V(8); PG8_WAIT_L(0); PG8_BAR; PG8_MMA(1, 0, At, B0); PG8_MMA(1, 1, At, B1); PG8_BAR; PG8_SCHED;
;             PG8_LDB(B0, 1, 0); PG8_LDB(B1, 1, 1); PG8_SCHED; PG8_LDA(At, 1, 0); PG8_STAGE(PG8_SA(0, 1), a2 + hstep, voffA);
;             PG8_WAIT_V(8); PG8_WAIT_L(0); PG8_BAR; PG8_MMA(0, 0, At, B0); PG8_MMA(0, 1, At, B1); PG8_BAR; PG8_SCHED;
	v_mfma_f32_16x16x32_bf16 v[62:65], v[144:147], v[188:191], 0
	v_mfma_f32_16x16x32_bf16 v[62:65], v[160:163], v[206:209], v[62:65]
	v_mfma_f32_16x16x32_bf16 v[58:61], v[168:171], v[206:209], 0
	v_mfma_f32_16x16x32_bf16 v[58:61], v[164:167], v[188:191], v[58:61]
	v_mfma_f32_16x16x32_bf16 v[42:45], v[164:167], v[210:213], 0
	v_mfma_f32_16x16x32_bf16 v[42:45], v[168:171], v[214:217], v[42:45]
	v_mfma_f32_16x16x32_bf16 v[46:49], v[160:163], v[214:217], 0
	v_mfma_f32_16x16x32_bf16 v[46:49], v[144:147], v[210:213], v[46:49]
	v_mfma_f32_16x16x32_bf16 v[30:33], v[144:147], v[218:221], 0
	v_mfma_f32_16x16x32_bf16 v[30:33], v[160:163], v[222:225], v[30:33]
	v_mfma_f32_16x16x32_bf16 v[26:29], v[168:171], v[222:225], 0
	v_mfma_f32_16x16x32_bf16 v[26:29], v[164:167], v[218:221], v[26:29]
	v_mfma_f32_16x16x32_bf16 v[10:13], v[164:167], v[226:229], 0
	v_mfma_f32_16x16x32_bf16 v[10:13], v[168:171], v[230:233], v[10:13]
	v_mfma_f32_16x16x32_bf16 v[14:17], v[160:163], v[230:233], 0
	v_mfma_f32_16x16x32_bf16 v[14:17], v[144:147], v[226:229], v[14:17]
	v_mfma_f32_16x16x32_bf16 v[54:57], v[172:175], v[188:191], 0
	v_mfma_f32_16x16x32_bf16 v[54:57], v[176:179], v[206:209], v[54:57]
	v_mfma_f32_16x16x32_bf16 v[50:53], v[184:187], v[206:209], 0
	v_mfma_f32_16x16x32_bf16 v[50:53], v[180:183], v[188:191], v[50:53]
	v_mfma_f32_16x16x32_bf16 v[34:37], v[180:183], v[210:213], 0
	v_mfma_f32_16x16x32_bf16 v[34:37], v[184:187], v[214:217], v[34:37]
	v_mfma_f32_16x16x32_bf16 v[38:41], v[176:179], v[214:217], 0
	v_mfma_f32_16x16x32_bf16 v[38:41], v[172:175], v[210:213], v[38:41]
	v_mfma_f32_16x16x32_bf16 v[22:25], v[172:175], v[218:221], 0
	v_mfma_f32_16x16x32_bf16 v[22:25], v[176:179], v[222:225], v[22:25]
	v_mfma_f32_16x16x32_bf16 v[18:21], v[184:187], v[222:225], 0
	v_mfma_f32_16x16x32_bf16 v[18:21], v[180:183], v[218:221], v[18:21]
	v_mfma_f32_16x16x32_bf16 v[2:5], v[180:183], v[226:229], 0
	v_mfma_f32_16x16x32_bf16 v[2:5], v[184:187], v[230:233], v[2:5]
	v_mfma_f32_16x16x32_bf16 v[6:9], v[176:179], v[230:233], 0
	v_mfma_f32_16x16x32_bf16 v[6:9], v[172:175], v[226:229], v[6:9]
	s_barrier
	s_add_i32 s72, 0, 0x18000
	v_add_u32_e32 v153, s72, v150
	s_add_i32 s73, 0, 0x1c000
	ds_read_b128 v[144:147], v153
	ds_read_b128 v[160:163], v153 offset:1024
	ds_read_b128 v[164:167], v153 offset:2048
	ds_read_b128 v[168:171], v153 offset:3072
	v_add_u32_e32 v153, s73, v150
	ds_read_b128 v[172:175], v153
	ds_read_b128 v[176:179], v153 offset:1024
	ds_read_b128 v[180:183], v153 offset:2048
	ds_read_b128 v[184:187], v153 offset:3072
	s_add_u32 s24, s46, 0x40000
	s_addc_u32 s25, s47, 0
	s_mov_b32 m0, s57
	v_lshl_add_u64 v[236:237], s[24:25], 0, v[130:131]
	ds_read_b128 v[188:191], v152 offset:32768
	ds_read_b128 v[206:209], v152 offset:33792
	ds_read_b128 v[210:213], v152 offset:34816
	ds_read_b128 v[214:217], v152 offset:35840
	ds_read_b128 v[218:221], v152 offset:36864
	ds_read_b128 v[222:225], v152 offset:37888
	ds_read_b128 v[226:229], v152 offset:38912
	ds_read_b128 v[230:233], v152 offset:39936
	global_load_lds_dwordx4 v[236:237], off
	v_lshl_add_u64 v[236:237], s[24:25], 0, v[134:135]
	s_mov_b32 m0, s58
	s_nop 0
	global_load_lds_dwordx4 v[236:237], off
	s_waitcnt vmcnt(8)
	s_waitcnt lgkmcnt(0)
	s_barrier
	v_mfma_f32_16x16x32_bf16 v[126:129], v[144:147], v[188:191], v[126:129]
	v_mfma_f32_16x16x32_bf16 v[126:129], v[160:163], v[206:209], v[126:129]
	v_mfma_f32_16x16x32_bf16 v[122:125], v[168:171], v[206:209], v[122:125]
	v_mfma_f32_16x16x32_bf16 v[122:125], v[164:167], v[188:191], v[122:125]
	v_mfma_f32_16x16x32_bf16 v[106:109], v[164:167], v[210:213], v[106:109]
	v_mfma_f32_16x16x32_bf16 v[106:109], v[168:171], v[214:217], v[106:109]
	v_mfma_f32_16x16x32_bf16 v[110:113], v[160:163], v[214:217], v[110:113]
	v_mfma_f32_16x16x32_bf16 v[110:113], v[144:147], v[210:213], v[110:113]
	v_mfma_f32_16x16x32_bf16 v[94:97], v[144:147], v[218:221], v[94:97]
	v_mfma_f32_16x16x32_bf16 v[94:97], v[160:163], v[222:225], v[94:97]
	v_mfma_f32_16x16x32_bf16 v[90:93], v[168:171], v[222:225], v[90:93]
	v_mfma_f32_16x16x32_bf16 v[90:93], v[164:167], v[218:221], v[90:93]
	v_mfma_f32_16x16x32_bf16 v[74:77], v[164:167], v[226:229], v[74:77]
	v_mfma_f32_16x16x32_bf16 v[74:77], v[168:171], v[230:233], v[74:77]
	v_mfma_f32_16x16x32_bf16 v[78:81], v[160:163], v[230:233], v[78:81]
	v_mfma_f32_16x16x32_bf16 v[78:81], v[144:147], v[226:229], v[78:81]
	v_mfma_f32_16x16x32_bf16 v[118:121], v[172:175], v[188:191], v[118:121]
	v_mfma_f32_16x16x32_bf16 v[118:121], v[176:179], v[206:209], v[118:121]
	v_mfma_f32_16x16x32_bf16 v[114:117], v[184:187], v[206:209], v[114:117]
	v_mfma_f32_16x16x32_bf16 v[114:117], v[180:183], v[188:191], v[114:117]
	v_mfma_f32_16x16x32_bf16 v[98:101], v[180:183], v[210:213], v[98:101]
	v_mfma_f32_16x16x32_bf16 v[98:101], v[184:187], v[214:217], v[98:101]
	v_mfma_f32_16x16x32_bf16 v[102:105], v[176:179], v[214:217], v[102:105]
	v_mfma_f32_16x16x32_bf16 v[102:105], v[172:175], v[210:213], v[102:105]
	v_mfma_f32_16x16x32_bf16 v[86:89], v[172:175], v[218:221], v[86:89]
	v_mfma_f32_16x16x32_bf16 v[86:89], v[176:179], v[222:225], v[86:89]
	v_mfma_f32_16x16x32_bf16 v[82:85], v[184:187], v[222:225], v[82:85]
	v_mfma_f32_16x16x32_bf16 v[82:85], v[180:183], v[218:221], v[82:85]
	v_mfma_f32_16x16x32_bf16 v[66:69], v[180:183], v[226:229], v[66:69]
	v_mfma_f32_16x16x32_bf16 v[66:69], v[184:187], v[230:233], v[66:69]
	v_mfma_f32_16x16x32_bf16 v[70:73], v[176:179], v[230:233], v[70:73]
	v_mfma_f32_16x16x32_bf16 v[70:73], v[172:175], v[226:229], v[70:73]
	s_barrier
; #define PG8_STAGE(bufoff, gbase, voff) do { _Pragma("unroll") for (int _i = 0; _i < 2; ++_i) \
;         __builtin_amdgcn_global_load_lds((const unsigned*)((const char*)(gbase) + (voff)[_i]), (PG8_LAS unsigned*)(lds + (bufoff) + ldsw + _i * 8192), 16, 0, 0); } while (0)
; #define PG8_LDA(dst, b, h) do { _Pragma("unroll") for (int m = 0; m < 4; ++m) _Pragma("unroll") for (int k = 0; k < 2; ++k) dst[m][k] = *(const PG8_LAS bf16x8*)(lds + PG8_SA(b, h) + aoff + m * 2048 + k * 1024); } while (0)
; #define PG8_MMA(ai, bj, At, Bt) do { __builtin_amdgcn_s_setprio(1); _Pragma("unroll") for (int m = 0; m < 4; ++m) _Pragma("unroll") for (int n = 0; n < 2; ++n) _Pragma("unroll") for (int k = 0; k < 2; ++k) \
;         acc[ai][bj][m][n] = __builtin_amdgcn_mfma_f32_16x16x32_bf16(Bt[n][k], At[m][k], acc[ai][bj][m][n], 0, 0, 0); __builtin_amdgcn_s_setprio(0); } while (0)
; #define PG8_WAIT_V(n) asm volatile("s_waitcnt vmcnt(" #n ")" ::: "memory")
; #define PG8_WAIT_L(n) asm volatile("s_waitcnt lgkmcnt(" #n ")" ::: "memory")
; #define PG8_BAR __builtin_amdgcn_s_barrier()
; #define PG8_SCHED __builtin_amdgcn_sched_barrier(0)
; template <class Epi, class Sched, bool ALIGN_EPI = false, bool SP2 = false>
; __device__ __forceinline__ void gemm_phase(PG8_LAS unsigned char* lds, const Gemm g, const Sched& S, const Epi& E) {
;     ...
;             PG8_LDA(At, 1, 1); PG8_STAGE(PG8_SB(1, 0), b3, voffB); PG8_STAGE(PG8_SB(1, 1), b3 + hstep, voffB); PG8_STAGE(PG8_SA(1, 0), a3, voffA);
;             PG8_WAIT_V(8); PG8_WAIT_L(0); PG8_BAR; PG8_MMA(1, 0, At, B0); PG8_MMA(1, 1, At, B1); PG8_BAR; PG8_SCHED;
	s_add_i32 s24, s72, s51
	v_lshl_add_u64 v[148:149], v[148:149], 0, s[38:39]
	s_mov_b32 m0, s24
	ds_read_b128 v[188:191], v152 offset:49152
	ds_read_b128 v[206:209], v152 offset:50176
	ds_read_b128 v[210:213], v152 offset:51200
	ds_read_b128 v[214:217], v152 offset:52224
	ds_read_b128 v[218:221], v152 offset:53248
	ds_read_b128 v[222:225], v152 offset:54272
	ds_read_b128 v[226:229], v152 offset:55296
	ds_read_b128 v[230:233], v152 offset:56320
	global_load_lds_dwordx4 v[148:149], off
	s_add_i32 m0, s24, 0x2000
	s_add_u32 s24, s42, 0x40080
	v_lshl_add_u64 v[148:149], v[234:235], 0, s[38:39]
	s_addc_u32 s25, s43, 0
	s_add_i32 s42, s73, s51
	global_load_lds_dwordx4 v[148:149], off
	v_lshl_add_u64 v[148:149], s[24:25], 0, v[132:133]
	s_mov_b32 m0, s42
	s_nop 0
	global_load_lds_dwordx4 v[148:149], off
	v_lshl_add_u64 v[148:149], s[24:25], 0, v[136:137]
	s_add_i32 m0, s42, 0x2000
	s_nop 0
	global_load_lds_dwordx4 v[148:149], off
	v_lshl_add_u64 v[148:149], s[26:27], 0, v[130:131]
	s_mov_b32 m0, s64
	s_nop 0
	global_load_lds_dwordx4 v[148:149], off
	v_lshl_add_u64 v[148:149], s[26:27], 0, v[134:135]
	s_mov_b32 m0, s65
	s_nop 0
	global_load_lds_dwordx4 v[148:149], off
	s_waitcnt vmcnt(8)
	s_waitcnt lgkmcnt(0)
	s_barrier
	v_mfma_f32_16x16x32_bf16 v[62:65], v[144:147], v[188:191], v[62:65]
	v_mfma_f32_16x16x32_bf16 v[62:65], v[160:163], v[206:209], v[62:65]
	v_mfma_f32_16x16x32_bf16 v[58:61], v[168:171], v[206:209], v[58:61]
	v_mfma_f32_16x16x32_bf16 v[58:61], v[164:167], v[188:191], v[58:61]
	v_mfma_f32_16x16x32_bf16 v[42:45], v[164:167], v[210:213], v[42:45]
	v_mfma_f32_16x16x32_bf16 v[42:45], v[168:171], v[214:217], v[42:45]
	v_mfma_f32_16x16x32_bf16 v[46:49], v[160:163], v[214:217], v[46:49]
	v_mfma_f32_16x16x32_bf16 v[46:49], v[144:147], v[210:213], v[46:49]
	v_mfma_f32_16x16x32_bf16 v[30:33], v[144:147], v[218:221], v[30:33]
	v_mfma_f32_16x16x32_bf16 v[30:33], v[160:163], v[222:225], v[30:33]
	v_mfma_f32_16x16x32_bf16 v[26:29], v[168:171], v[222:225], v[26:29]
	v_mfma_f32_16x16x32_bf16 v[26:29], v[164:167], v[218:221], v[26:29]
	v_mfma_f32_16x16x32_bf16 v[10:13], v[164:167], v[226:229], v[10:13]
	v_mfma_f32_16x16x32_bf16 v[10:13], v[168:171], v[230:233], v[10:13]
	v_mfma_f32_16x16x32_bf16 v[14:17], v[160:163], v[230:233], v[14:17]
	v_mfma_f32_16x16x32_bf16 v[14:17], v[144:147], v[226:229], v[14:17]
	v_mfma_f32_16x16x32_bf16 v[54:57], v[172:175], v[188:191], v[54:57]
	v_mfma_f32_16x16x32_bf16 v[54:57], v[176:179], v[206:209], v[54:57]
	v_mfma_f32_16x16x32_bf16 v[50:53], v[184:187], v[206:209], v[50:53]
	v_mfma_f32_16x16x32_bf16 v[50:53], v[180:183], v[188:191], v[50:53]
	v_mfma_f32_16x16x32_bf16 v[34:37], v[180:183], v[210:213], v[34:37]
	v_mfma_f32_16x16x32_bf16 v[34:37], v[184:187], v[214:217], v[34:37]
	v_mfma_f32_16x16x32_bf16 v[38:41], v[176:179], v[214:217], v[38:41]
	v_mfma_f32_16x16x32_bf16 v[38:41], v[172:175], v[210:213], v[38:41]
	v_mfma_f32_16x16x32_bf16 v[22:25], v[172:175], v[218:221], v[22:25]
	v_mfma_f32_16x16x32_bf16 v[22:25], v[176:179], v[222:225], v[22:25]
	v_mfma_f32_16x16x32_bf16 v[18:21], v[184:187], v[222:225], v[18:21]
	v_mfma_f32_16x16x32_bf16 v[18:21], v[180:183], v[218:221], v[18:21]
	v_mfma_f32_16x16x32_bf16 v[2:5], v[180:183], v[226:229], v[2:5]
	v_mfma_f32_16x16x32_bf16 v[2:5], v[184:187], v[230:233], v[2:5]
	v_mfma_f32_16x16x32_bf16 v[6:9], v[176:179], v[230:233], v[6:9]
	v_mfma_f32_16x16x32_bf16 v[6:9], v[172:175], v[226:229], v[6:9]
	s_barrier
	s_add_i32 s71, s71, 2
	s_add_u32 s69, s69, 0x100
	s_addc_u32 s70, s70, 0
	s_cmp_gt_u32 s71, 13
	s_mov_b64 s[24:25], s[2:3]
	s_cbranch_scc1 .Lpeel_exit_0

; #define PG8_BAR __builtin_amdgcn_s_barrier()
; template <class Epi, class Sched, bool ALIGN_EPI = false, bool SP2 = false>
; __device__ __forceinline__ void gemm_phase(PG8_LAS unsigned char* lds, const Gemm g, const Sched& S, const Epi& E) {
;     ...
;         if constexpr (ALIGN_EPI) { if (wr == 0) PG8_BAR; }
.Lpeel_exit_0:
	s_and_b64 vcc, exec, s[6:7]
	s_cbranch_vccz .LBB0_241
	s_barrier

; #define PG8_STAGE(bufoff, gbase, voff) do { _Pragma("unroll") for (int _i = 0; _i < 2; ++_i) \
;         __builtin_amdgcn_global_load_lds((const unsigned*)((const char*)(gbase) + (voff)[_i]), (PG8_LAS unsigned*)(lds + (bufoff) + ldsw + _i * 8192), 16, 0, 0); } while (0)
; #define PG8_LDA(dst, b, h) do { _Pragma("unroll") for (int m = 0; m < 4; ++m) _Pragma("unroll") for (int k = 0; k < 2; ++k) dst[m][k] = *(const PG8_LAS bf16x8*)(lds + PG8_SA(b, h) + aoff + m * 2048 + k * 1024); } while (0)
; #define PG8_LDB(dst, b, h) do { _Pragma("unroll") for (int n = 0; n < 2; ++n) _Pragma("unroll") for (int k = 0; k < 2; ++k) dst[n][k] = *(const PG8_LAS bf16x8*)(lds + PG8_SB(b, h) + boff + n * 2048 + k * 1024); } while (0)
; #define PG8_MMA(ai, bj, At, Bt) do { __builtin_amdgcn_s_setprio(1); _Pragma("unroll") for (int m = 0; m < 4; ++m) _Pragma("unroll") for (int n = 0; n < 2; ++n) _Pragma("unroll") for (int k = 0; k < 2; ++k) \
;         acc[ai][bj][m][n] = __builtin_amdgcn_mfma_f32_16x16x32_bf16(Bt[n][k], At[m][k], acc[ai][bj][m][n], 0, 0, 0); __builtin_amdgcn_s_setprio(0); } while (0)
; #define PG8_WAIT_V(n) asm volatile("s_waitcnt vmcnt(" #n ")" ::: "memory")
; template <class Epi, class Sched, bool ALIGN_EPI = false, bool SP2 = false>
; __device__ __forceinline__ void gemm_phase(PG8_LAS unsigned char* lds, const Gemm g, const Sched& S, const Epi& E) {
;     ...
;         const char* nA = has_next ? (const char*)g.A + (size_t)nxt.pm * tstep : cA; const char* nB = has_next ? (const char*)g.Bt + (size_t)nxt.pn * tstep : cB;
;         for (int t = 0; t < nt; t += 2) {
;             const bool last = (t == nt - 2);
;             const char* a1 = cA + (size_t)(t + 1) * kstepA;
;             const char* a2 = last ? nA : cA + (size_t)(t + 2) * kstepA; const char* b2 = last ? nB : cB + (size_t)(t + 2) * kstep;
;             const char* a3 = a2 + kstepA; const char* b3 = b2 + kstep;
;             if (last && has_next) S.a_ready(nxt);
;             if constexpr (SP2) {
;             PG8_LDB(B0, 0, 0); PG8_LDB(B1, 0, 1); PG8_SCHED; PG8_LDA(At, 0, 0); PG8_STAGE(PG8_SA(1, 1), a1 + hstep, voffA);
;             PG8_WAIT_V(8); PG8_WAIT_L(0); PG8_BAR; PG8_MMA(0, 0, At, B0); PG8_MMA(0, 1, At, B1); PG8_BAR; PG8_SCHED;
;             PG8_LDA(At, 0, 1); PG8_STAGE(PG8_SB(0, 0), b2, voffB); PG8_STAGE(PG8_SB(0, 1), b2 + hstep, voffB); PG8_STAGE(PG8_SA(0, 0), a2, voffA);
.LBB0_309:
	s_add_u32 s47, s24, 0x100
	s_addc_u32 s48, s25, 0
	s_add_u32 s2, s26, 0x4000
	s_addc_u32 s3, s27, 0
	s_mov_b32 s24, 0
	s_add_i32 s49, s24, 2
	s_add_u32 s25, s2, 0x4000
	s_addc_u32 s26, s3, 0
	s_cmp_eq_u32 s59, s24
	s_cselect_b32 s27, s9, s26
	s_cselect_b32 s26, s8, s25
	s_cselect_b32 s66, s44, s47
	s_cselect_b32 s67, s45, s48
	s_add_u32 s24, s26, 0x4000
	s_addc_u32 s25, s27, 0
	s_add_i32 s65, 0, 0x14000
	v_add_u32_e32 v142, s76, v187
	v_add_u32_e32 v167, s65, v187
	ds_read_b128 v[130:133], v142
	ds_read_b128 v[134:137], v142 offset:1024
	ds_read_b128 v[138:141], v142 offset:2048
	ds_read_b128 v[142:145], v142 offset:3072
	ds_read_b128 v[146:149], v167
	ds_read_b128 v[150:153], v167 offset:1024
	ds_read_b128 v[206:209], v167 offset:2048
	ds_read_b128 v[210:213], v167 offset:3072
	v_lshl_add_u64 v[184:185], s[2:3], 0, v[182:183]
	s_add_i32 m0, s51, 0xc000
	ds_read_b128 v[214:217], v188
	ds_read_b128 v[218:221], v188 offset:1024
	ds_read_b128 v[222:225], v188 offset:2048
	ds_read_b128 v[226:229], v188 offset:3072
	ds_read_b128 v[230:233], v188 offset:4096
	ds_read_b128 v[234:237], v188 offset:5120
	ds_read_b128 v[238:241], v188 offset:6144
	ds_read_b128 v[242:245], v188 offset:7168
	global_load_lds_dwordx4 v[184:185], off
	v_lshl_add_u64 v[184:185], s[2:3], 0, v[180:181]
	s_add_i32 m0, s51, 0xe000
	s_nop 0
	global_load_lds_dwordx4 v[184:185], off
	s_waitcnt vmcnt(8)
	s_waitcnt lgkmcnt(0)
	s_barrier
	v_mfma_f32_16x16x32_bf16 v[126:129], v[130:133], v[214:217], 0
	v_mfma_f32_16x16x32_bf16 v[126:129], v[134:137], v[218:221], v[126:129]
	v_mfma_f32_16x16x32_bf16 v[122:125], v[142:145], v[218:221], 0
	v_mfma_f32_16x16x32_bf16 v[122:125], v[138:141], v[214:217], v[122:125]
	v_mfma_f32_16x16x32_bf16 v[106:109], v[138:141], v[222:225], 0
	v_mfma_f32_16x16x32_bf16 v[106:109], v[142:145], v[226:229], v[106:109]
	v_mfma_f32_16x16x32_bf16 v[110:113], v[134:137], v[226:229], 0
	v_mfma_f32_16x16x32_bf16 v[110:113], v[130:133], v[222:225], v[110:113]
	v_mfma_f32_16x16x32_bf16 v[94:97], v[130:133], v[230:233], 0
	v_mfma_f32_16x16x32_bf16 v[94:97], v[134:137], v[234:237], v[94:97]
	v_mfma_f32_16x16x32_bf16 v[90:93], v[142:145], v[234:237], 0
	v_mfma_f32_16x16x32_bf16 v[90:93], v[138:141], v[230:233], v[90:93]
	v_mfma_f32_16x16x32_bf16 v[74:77], v[138:141], v[238:241], 0
	v_mfma_f32_16x16x32_bf16 v[74:77], v[142:145], v[242:245], v[74:77]
	v_mfma_f32_16x16x32_bf16 v[78:81], v[134:137], v[242:245], 0
	v_mfma_f32_16x16x32_bf16 v[78:81], v[130:133], v[238:241], v[78:81]
	v_mfma_f32_16x16x32_bf16 v[118:121], v[146:149], v[214:217], 0
	v_mfma_f32_16x16x32_bf16 v[118:121], v[150:153], v[218:221], v[118:121]
	v_mfma_f32_16x16x32_bf16 v[114:117], v[210:213], v[218:221], 0
	v_mfma_f32_16x16x32_bf16 v[114:117], v[206:209], v[214:217], v[114:117]
	v_mfma_f32_16x16x32_bf16 v[98:101], v[206:209], v[222:225], 0
	v_mfma_f32_16x16x32_bf16 v[98:101], v[210:213], v[226:229], v[98:101]
	v_mfma_f32_16x16x32_bf16 v[102:105], v[150:153], v[226:229], 0
	v_mfma_f32_16x16x32_bf16 v[102:105], v[146:149], v[222:225], v[102:105]
	v_mfma_f32_16x16x32_bf16 v[86:89], v[146:149], v[230:233], 0
	v_mfma_f32_16x16x32_bf16 v[86:89], v[150:153], v[234:237], v[86:89]
	v_mfma_f32_16x16x32_bf16 v[82:85], v[210:213], v[234:237], 0
	v_mfma_f32_16x16x32_bf16 v[82:85], v[206:209], v[230:233], v[82:85]
	v_mfma_f32_16x16x32_bf16 v[66:69], v[206:209], v[238:241], 0
	v_mfma_f32_16x16x32_bf16 v[66:69], v[210:213], v[242:245], v[66:69]
	v_mfma_f32_16x16x32_bf16 v[70:73], v[150:153], v[242:245], 0
	v_mfma_f32_16x16x32_bf16 v[70:73], v[146:149], v[238:241], v[70:73]
	s_barrier
	s_add_i32 s68, s76, s50
	v_lshl_add_u64 v[184:185], s[66:67], 0, v[0:1]
	s_mov_b32 m0, s68
	ds_read_b128 v[214:217], v188 offset:16384
	ds_read_b128 v[218:221], v188 offset:17408
	ds_read_b128 v[222:225], v188 offset:18432
	ds_read_b128 v[226:229], v188 offset:19456
	ds_read_b128 v[230:233], v188 offset:20480
	ds_read_b128 v[234:237], v188 offset:21504
	ds_read_b128 v[238:241], v188 offset:22528
	ds_read_b128 v[242:245], v188 offset:23552
	global_load_lds_dwordx4 v[184:185], off
	s_add_i32 m0, s68, 0x2000
	v_lshl_add_u64 v[190:191], s[66:67], 0, v[164:165]
	s_add_u32 s66, s66, s12
	s_addc_u32 s67, s67, 0
	s_add_i32 s65, s65, s50
	global_load_lds_dwordx4 v[190:191], off
	v_lshl_add_u64 v[246:247], s[66:67], 0, v[0:1]
	s_mov_b32 m0, s65
	v_lshl_add_u64 v[248:249], s[66:67], 0, v[164:165]
	global_load_lds_dwordx4 v[246:247], off
	s_add_i32 m0, s65, 0x2000
	v_lshl_add_u64 v[250:251], s[26:27], 0, v[160:161]
	global_load_lds_dwordx4 v[248:249], off
	s_mov_b32 m0, s51
	s_nop 0
	global_load_lds_dwordx4 v[250:251], off
	v_lshl_add_u64 v[250:251], s[26:27], 0, v[162:163]
	s_mov_b32 m0, s52
	s_nop 0
	global_load_lds_dwordx4 v[250:251], off
	s_waitcnt vmcnt(8)
	s_waitcnt lgkmcnt(0)
	s_barrier
; #define PG8_STAGE(bufoff, gbase, voff) do { _Pragma("unroll") for (int _i = 0; _i < 2; ++_i) \
;         __builtin_amdgcn_global_load_lds((const unsigned*)((const char*)(gbase) + (voff)[_i]), (PG8_LAS unsigned*)(lds + (bufoff) + ldsw + _i * 8192), 16, 0, 0); } while (0)
; #define PG8_LDA(dst, b, h) do { _Pragma("unroll") for (int m = 0; m < 4; ++m) _Pragma("unroll") for (int k = 0; k < 2; ++k) dst[m][k] = *(const PG8_LAS bf16x8*)(lds + PG8_SA(b, h) + aoff + m * 2048 + k * 1024); } while (0)
; #define PG8_LDB(dst, b, h) do { _Pragma("unroll") for (int n = 0; n < 2; ++n) _Pragma("unroll") for (int k = 0; k < 2; ++k) dst[n][k] = *(const PG8_LAS bf16x8*)(lds + PG8_SB(b, h) + boff + n * 2048 + k * 1024); } while (0)
; #define PG8_MMA(ai, bj, At, Bt) do { __builtin_amdgcn_s_setprio(1); _Pragma("unroll") for (int m = 0; m < 4; ++m) _Pragma("unroll") for (int n = 0; n < 2; ++n) _Pragma("unroll") for (int k = 0; k < 2; ++k) \
;         acc[ai][bj][m][n] = __builtin_amdgcn_mfma_f32_16x16x32_bf16(Bt[n][k], At[m][k], acc[ai][bj][m][n], 0, 0, 0); __builtin_amdgcn_s_setprio(0); } while (0)
; #define PG8_WAIT_V(n) asm volatile("s_waitcnt vmcnt(" #n ")" ::: "memory")
; #define PG8_WAIT_L(n) asm volatile("s_waitcnt lgkmcnt(" #n ")" ::: "memory")
; #define PG8_BAR __builtin_amdgcn_s_barrier()
; #define PG8_SCHED __builtin_amdgcn_sched_barrier(0)
; template <class Epi, class Sched, bool ALIGN_EPI = false, bool SP2 = false>
; __device__ __forceinline__ void gemm_phase(PG8_LAS unsigned char* lds, const Gemm g, const Sched& S, const Epi& E) {
;     ...
;             PG8_WAIT_V(8); PG8_WAIT_L(0); PG8_BAR; PG8_MMA(1, 0, At, B0); PG8_MMA(1, 1, At, B1); PG8_BAR; PG8_SCHED;
;             PG8_LDB(B0, 1, 0); PG8_LDB(B1, 1, 1); PG8_SCHED; PG8_LDA(At, 1, 0); PG8_STAGE(PG8_SA(0, 1), a2 + hstep, voffA);
;             PG8_WAIT_V(8); PG8_WAIT_L(0); PG8_BAR; PG8_MMA(0, 0, At, B0); PG8_MMA(0, 1, At, B1); PG8_BAR; PG8_SCHED;
	v_mfma_f32_16x16x32_bf16 v[62:65], v[130:133], v[214:217], 0
	v_mfma_f32_16x16x32_bf16 v[62:65], v[134:137], v[218:221], v[62:65]
	v_mfma_f32_16x16x32_bf16 v[58:61], v[142:145], v[218:221], 0
	v_mfma_f32_16x16x32_bf16 v[58:61], v[138:141], v[214:217], v[58:61]
	v_mfma_f32_16x16x32_bf16 v[42:45], v[138:141], v[222:225], 0
	v_mfma_f32_16x16x32_bf16 v[42:45], v[142:145], v[226:229], v[42:45]
	v_mfma_f32_16x16x32_bf16 v[46:49], v[134:137], v[226:229], 0
	v_mfma_f32_16x16x32_bf16 v[46:49], v[130:133], v[222:225], v[46:49]
	v_mfma_f32_16x16x32_bf16 v[30:33], v[130:133], v[230:233], 0
	v_mfma_f32_16x16x32_bf16 v[30:33], v[134:137], v[234:237], v[30:33]
	v_mfma_f32_16x16x32_bf16 v[26:29], v[142:145], v[234:237], 0
	v_mfma_f32_16x16x32_bf16 v[26:29], v[138:141], v[230:233], v[26:29]
	v_mfma_f32_16x16x32_bf16 v[10:13], v[138:141], v[238:241], 0
	v_mfma_f32_16x16x32_bf16 v[10:13], v[142:145], v[242:245], v[10:13]
	v_mfma_f32_16x16x32_bf16 v[14:17], v[134:137], v[242:245], 0
	v_mfma_f32_16x16x32_bf16 v[14:17], v[130:133], v[238:241], v[14:17]
	v_mfma_f32_16x16x32_bf16 v[54:57], v[146:149], v[214:217], 0
	v_mfma_f32_16x16x32_bf16 v[54:57], v[150:153], v[218:221], v[54:57]
	v_mfma_f32_16x16x32_bf16 v[50:53], v[210:213], v[218:221], 0
	v_mfma_f32_16x16x32_bf16 v[50:53], v[206:209], v[214:217], v[50:53]
	v_mfma_f32_16x16x32_bf16 v[34:37], v[206:209], v[222:225], 0
	v_mfma_f32_16x16x32_bf16 v[34:37], v[210:213], v[226:229], v[34:37]
	v_mfma_f32_16x16x32_bf16 v[38:41], v[150:153], v[226:229], 0
	v_mfma_f32_16x16x32_bf16 v[38:41], v[146:149], v[222:225], v[38:41]
	v_mfma_f32_16x16x32_bf16 v[22:25], v[146:149], v[230:233], 0
	v_mfma_f32_16x16x32_bf16 v[22:25], v[150:153], v[234:237], v[22:25]
	v_mfma_f32_16x16x32_bf16 v[18:21], v[210:213], v[234:237], 0
	v_mfma_f32_16x16x32_bf16 v[18:21], v[206:209], v[230:233], v[18:21]
	v_mfma_f32_16x16x32_bf16 v[2:5], v[206:209], v[238:241], 0
	v_mfma_f32_16x16x32_bf16 v[2:5], v[210:213], v[242:245], v[2:5]
	v_mfma_f32_16x16x32_bf16 v[6:9], v[150:153], v[242:245], 0
	v_mfma_f32_16x16x32_bf16 v[6:9], v[146:149], v[238:241], v[6:9]
	s_barrier
	s_add_i32 s65, 0, 0x18000
	s_add_i32 s66, 0, 0x1c000
	v_add_u32_e32 v142, s65, v187
	v_add_u32_e32 v167, s66, v187
	ds_read_b128 v[130:133], v142
	ds_read_b128 v[134:137], v142 offset:1024
	ds_read_b128 v[138:141], v142 offset:2048
	ds_read_b128 v[142:145], v142 offset:3072
	ds_read_b128 v[146:149], v167
	ds_read_b128 v[150:153], v167 offset:1024
	ds_read_b128 v[206:209], v167 offset:2048
	ds_read_b128 v[210:213], v167 offset:3072
	s_add_u32 s26, s26, s12
	s_addc_u32 s27, s27, 0
	s_mov_b32 m0, s53
	v_lshl_add_u64 v[250:251], s[26:27], 0, v[160:161]
	ds_read_b128 v[214:217], v188 offset:32768
	ds_read_b128 v[218:221], v188 offset:33792
	ds_read_b128 v[222:225], v188 offset:34816
	ds_read_b128 v[226:229], v188 offset:35840
	ds_read_b128 v[230:233], v188 offset:36864
	ds_read_b128 v[234:237], v188 offset:37888
	ds_read_b128 v[238:241], v188 offset:38912
	ds_read_b128 v[242:245], v188 offset:39936
	global_load_lds_dwordx4 v[250:251], off
	v_lshl_add_u64 v[250:251], s[26:27], 0, v[162:163]
	s_mov_b32 m0, s54
	s_nop 0
	global_load_lds_dwordx4 v[250:251], off
	s_waitcnt vmcnt(8)
	s_waitcnt lgkmcnt(0)
	s_barrier
	v_mfma_f32_16x16x32_bf16 v[126:129], v[130:133], v[214:217], v[126:129]
	v_mfma_f32_16x16x32_bf16 v[126:129], v[134:137], v[218:221], v[126:129]
	v_mfma_f32_16x16x32_bf16 v[122:125], v[142:145], v[218:221], v[122:125]
	v_mfma_f32_16x16x32_bf16 v[122:125], v[138:141], v[214:217], v[122:125]
	v_mfma_f32_16x16x32_bf16 v[106:109], v[138:141], v[222:225], v[106:109]
	v_mfma_f32_16x16x32_bf16 v[106:109], v[142:145], v[226:229], v[106:109]
	v_mfma_f32_16x16x32_bf16 v[110:113], v[134:137], v[226:229], v[110:113]
	v_mfma_f32_16x16x32_bf16 v[110:113], v[130:133], v[222:225], v[110:113]
	v_mfma_f32_16x16x32_bf16 v[94:97], v[130:133], v[230:233], v[94:97]
	v_mfma_f32_16x16x32_bf16 v[94:97], v[134:137], v[234:237], v[94:97]
	v_mfma_f32_16x16x32_bf16 v[90:93], v[142:145], v[234:237], v[90:93]
	v_mfma_f32_16x16x32_bf16 v[90:93], v[138:141], v[230:233], v[90:93]
	v_mfma_f32_16x16x32_bf16 v[74:77], v[138:141], v[238:241], v[74:77]
	v_mfma_f32_16x16x32_bf16 v[74:77], v[142:145], v[242:245], v[74:77]
	v_mfma_f32_16x16x32_bf16 v[78:81], v[134:137], v[242:245], v[78:81]
	v_mfma_f32_16x16x32_bf16 v[78:81], v[130:133], v[238:241], v[78:81]
	v_mfma_f32_16x16x32_bf16 v[118:121], v[146:149], v[214:217], v[118:121]
	v_mfma_f32_16x16x32_bf16 v[118:121], v[150:153], v[218:221], v[118:121]
	v_mfma_f32_16x16x32_bf16 v[114:117], v[210:213], v[218:221], v[114:117]
	v_mfma_f32_16x16x32_bf16 v[114:117], v[206:209], v[214:217], v[114:117]
	v_mfma_f32_16x16x32_bf16 v[98:101], v[206:209], v[222:225], v[98:101]
	v_mfma_f32_16x16x32_bf16 v[98:101], v[210:213], v[226:229], v[98:101]
	v_mfma_f32_16x16x32_bf16 v[102:105], v[150:153], v[226:229], v[102:105]
	v_mfma_f32_16x16x32_bf16 v[102:105], v[146:149], v[222:225], v[102:105]
	v_mfma_f32_16x16x32_bf16 v[86:89], v[146:149], v[230:233], v[86:89]
	v_mfma_f32_16x16x32_bf16 v[86:89], v[150:153], v[234:237], v[86:89]
	v_mfma_f32_16x16x32_bf16 v[82:85], v[210:213], v[234:237], v[82:85]
	v_mfma_f32_16x16x32_bf16 v[82:85], v[206:209], v[230:233], v[82:85]
	v_mfma_f32_16x16x32_bf16 v[66:69], v[206:209], v[238:241], v[66:69]
	v_mfma_f32_16x16x32_bf16 v[66:69], v[210:213], v[242:245], v[66:69]
	v_mfma_f32_16x16x32_bf16 v[70:73], v[150:153], v[242:245], v[70:73]
	v_mfma_f32_16x16x32_bf16 v[70:73], v[146:149], v[238:241], v[70:73]
	s_barrier
; #define PG8_STAGE(bufoff, gbase, voff) do { _Pragma("unroll") for (int _i = 0; _i < 2; ++_i) \
;         __builtin_amdgcn_global_load_lds((const unsigned*)((const char*)(gbase) + (voff)[_i]), (PG8_LAS unsigned*)(lds + (bufoff) + ldsw + _i * 8192), 16, 0, 0); } while (0)
; #define PG8_LDA(dst, b, h) do { _Pragma("unroll") for (int m = 0; m < 4; ++m) _Pragma("unroll") for (int k = 0; k < 2; ++k) dst[m][k] = *(const PG8_LAS bf16x8*)(lds + PG8_SA(b, h) + aoff + m * 2048 + k * 1024); } while (0)
; #define PG8_MMA(ai, bj, At, Bt) do { __builtin_amdgcn_s_setprio(1); _Pragma("unroll") for (int m = 0; m < 4; ++m) _Pragma("unroll") for (int n = 0; n < 2; ++n) _Pragma("unroll") for (int k = 0; k < 2; ++k) \
;         acc[ai][bj][m][n] = __builtin_amdgcn_mfma_f32_16x16x32_bf16(Bt[n][k], At[m][k], acc[ai][bj][m][n], 0, 0, 0); __builtin_amdgcn_s_setprio(0); } while (0)
; #define PG8_WAIT_V(n) asm volatile("s_waitcnt vmcnt(" #n ")" ::: "memory")
; #define PG8_WAIT_L(n) asm volatile("s_waitcnt lgkmcnt(" #n ")" ::: "memory")
; #define PG8_BAR __builtin_amdgcn_s_barrier()
; #define PG8_SCHED __builtin_amdgcn_sched_barrier(0)
; template <class Epi, class Sched, bool ALIGN_EPI = false, bool SP2 = false>
; __device__ __forceinline__ void gemm_phase(PG8_LAS unsigned char* lds, const Gemm g, const Sched& S, const Epi& E) {
;     ...
;             PG8_LDA(At, 1, 1); PG8_STAGE(PG8_SB(1, 0), b3, voffB); PG8_STAGE(PG8_SB(1, 1), b3 + hstep, voffB); PG8_STAGE(PG8_SA(1, 0), a3, voffA);
;             PG8_WAIT_V(8); PG8_WAIT_L(0); PG8_BAR; PG8_MMA(1, 0, At, B0); PG8_MMA(1, 1, At, B1); PG8_BAR; PG8_SCHED;
	s_add_i32 s26, s65, s50
	v_lshl_add_u64 v[184:185], v[184:185], 0, s[38:39]
	s_mov_b32 m0, s26
	ds_read_b128 v[214:217], v188 offset:49152
	ds_read_b128 v[218:221], v188 offset:50176
	ds_read_b128 v[222:225], v188 offset:51200
	ds_read_b128 v[226:229], v188 offset:52224
	ds_read_b128 v[230:233], v188 offset:53248
	ds_read_b128 v[234:237], v188 offset:54272
	ds_read_b128 v[238:241], v188 offset:55296
	ds_read_b128 v[242:245], v188 offset:56320
	global_load_lds_dwordx4 v[184:185], off
	v_lshl_add_u64 v[184:185], v[190:191], 0, s[38:39]
	s_add_i32 m0, s26, 0x2000
	s_add_i32 s26, s66, s50
	global_load_lds_dwordx4 v[184:185], off
	v_lshl_add_u64 v[184:185], v[246:247], 0, s[38:39]
	s_mov_b32 m0, s26
	s_nop 0
	global_load_lds_dwordx4 v[184:185], off
	v_lshl_add_u64 v[184:185], v[248:249], 0, s[38:39]
	s_add_i32 m0, s26, 0x2000
	s_nop 0
	global_load_lds_dwordx4 v[184:185], off
	v_lshl_add_u64 v[184:185], s[24:25], 0, v[160:161]
	s_mov_b32 m0, s56
	s_nop 0
	global_load_lds_dwordx4 v[184:185], off
	v_lshl_add_u64 v[184:185], s[24:25], 0, v[162:163]
	s_mov_b32 m0, s57
	s_nop 0
	global_load_lds_dwordx4 v[184:185], off
	s_waitcnt vmcnt(8)
	s_waitcnt lgkmcnt(0)
	s_barrier
	v_mfma_f32_16x16x32_bf16 v[62:65], v[130:133], v[214:217], v[62:65]
	v_mfma_f32_16x16x32_bf16 v[62:65], v[134:137], v[218:221], v[62:65]
	v_mfma_f32_16x16x32_bf16 v[58:61], v[142:145], v[218:221], v[58:61]
	v_mfma_f32_16x16x32_bf16 v[58:61], v[138:141], v[214:217], v[58:61]
	v_mfma_f32_16x16x32_bf16 v[42:45], v[138:141], v[222:225], v[42:45]
	v_mfma_f32_16x16x32_bf16 v[42:45], v[142:145], v[226:229], v[42:45]
	v_mfma_f32_16x16x32_bf16 v[46:49], v[134:137], v[226:229], v[46:49]
	v_mfma_f32_16x16x32_bf16 v[46:49], v[130:133], v[222:225], v[46:49]
	v_mfma_f32_16x16x32_bf16 v[30:33], v[130:133], v[230:233], v[30:33]
	v_mfma_f32_16x16x32_bf16 v[30:33], v[134:137], v[234:237], v[30:33]
	v_mfma_f32_16x16x32_bf16 v[26:29], v[142:145], v[234:237], v[26:29]
	v_mfma_f32_16x16x32_bf16 v[26:29], v[138:141], v[230:233], v[26:29]
	v_mfma_f32_16x16x32_bf16 v[10:13], v[138:141], v[238:241], v[10:13]
	v_mfma_f32_16x16x32_bf16 v[10:13], v[142:145], v[242:245], v[10:13]
	v_mfma_f32_16x16x32_bf16 v[14:17], v[134:137], v[242:245], v[14:17]
	v_mfma_f32_16x16x32_bf16 v[14:17], v[130:133], v[238:241], v[14:17]
	v_mfma_f32_16x16x32_bf16 v[54:57], v[146:149], v[214:217], v[54:57]
	v_mfma_f32_16x16x32_bf16 v[54:57], v[150:153], v[218:221], v[54:57]
	v_mfma_f32_16x16x32_bf16 v[50:53], v[210:213], v[218:221], v[50:53]
	v_mfma_f32_16x16x32_bf16 v[50:53], v[206:209], v[214:217], v[50:53]
	v_mfma_f32_16x16x32_bf16 v[34:37], v[206:209], v[222:225], v[34:37]
	v_mfma_f32_16x16x32_bf16 v[34:37], v[210:213], v[226:229], v[34:37]
	v_mfma_f32_16x16x32_bf16 v[38:41], v[150:153], v[226:229], v[38:41]
	v_mfma_f32_16x16x32_bf16 v[38:41], v[146:149], v[222:225], v[38:41]
	v_mfma_f32_16x16x32_bf16 v[22:25], v[146:149], v[230:233], v[22:25]
	v_mfma_f32_16x16x32_bf16 v[22:25], v[150:153], v[234:237], v[22:25]
	v_mfma_f32_16x16x32_bf16 v[18:21], v[210:213], v[234:237], v[18:21]
	v_mfma_f32_16x16x32_bf16 v[18:21], v[206:209], v[230:233], v[18:21]
	v_mfma_f32_16x16x32_bf16 v[2:5], v[206:209], v[238:241], v[2:5]
	v_mfma_f32_16x16x32_bf16 v[2:5], v[210:213], v[242:245], v[2:5]
	v_mfma_f32_16x16x32_bf16 v[6:9], v[150:153], v[242:245], v[6:9]
	v_mfma_f32_16x16x32_bf16 v[6:9], v[146:149], v[238:241], v[6:9]
	s_barrier
	s_add_u32 s47, s47, 0x100
	s_addc_u32 s48, s48, 0
	s_add_u32 s2, s2, 0x8000
	s_addc_u32 s3, s3, 0
	s_cmp_ge_u32 s49, s55
	s_mov_b32 s24, s49
	s_cbranch_scc1 .Lpeel_exit_1

; #define PG8_BAR __builtin_amdgcn_s_barrier()
; template <class Epi, class Sched, bool ALIGN_EPI = false, bool SP2 = false>
; __device__ __forceinline__ void gemm_phase(PG8_LAS unsigned char* lds, const Gemm g, const Sched& S, const Epi& E) {
;     ...
;         if constexpr (ALIGN_EPI) { if (wr == 0) PG8_BAR; }
.Lpeel_exit_1:
	s_and_b64 vcc, exec, s[42:43]
	s_cbranch_vccz .LBB0_313
	s_barrier

; #define PG8_STAGE(bufoff, gbase, voff) do { _Pragma("unroll") for (int _i = 0; _i < 2; ++_i) \
;         __builtin_amdgcn_global_load_lds((const unsigned*)((const char*)(gbase) + (voff)[_i]), (PG8_LAS unsigned*)(lds + (bufoff) + ldsw + _i * 8192), 16, 0, 0); } while (0)
; #define PG8_LDA(dst, b, h) do { _Pragma("unroll") for (int m = 0; m < 4; ++m) _Pragma("unroll") for (int k = 0; k < 2; ++k) dst[m][k] = *(const PG8_LAS bf16x8*)(lds + PG8_SA(b, h) + aoff + m * 2048 + k * 1024); } while (0)
; #define PG8_LDB(dst, b, h) do { _Pragma("unroll") for (int n = 0; n < 2; ++n) _Pragma("unroll") for (int k = 0; k < 2; ++k) dst[n][k] = *(const PG8_LAS bf16x8*)(lds + PG8_SB(b, h) + boff + n * 2048 + k * 1024); } while (0)
; #define PG8_MMA(ai, bj, At, Bt) do { __builtin_amdgcn_s_setprio(1); _Pragma("unroll") for (int m = 0; m < 4; ++m) _Pragma("unroll") for (int n = 0; n < 2; ++n) _Pragma("unroll") for (int k = 0; k < 2; ++k) \
;         acc[ai][bj][m][n] = __builtin_amdgcn_mfma_f32_16x16x32_bf16(Bt[n][k], At[m][k], acc[ai][bj][m][n], 0, 0, 0); __builtin_amdgcn_s_setprio(0); } while (0)
; #define PG8_WAIT_V(n) asm volatile("s_waitcnt vmcnt(" #n ")" ::: "memory")
; template <class Epi, class Sched, bool ALIGN_EPI = false, bool SP2 = false>
; __device__ __forceinline__ void gemm_phase(PG8_LAS unsigned char* lds, const Gemm g, const Sched& S, const Epi& E) {
;     ...
;         const char* nA = has_next ? (const char*)g.A + (size_t)nxt.pm * tstep : cA; const char* nB = has_next ? (const char*)g.Bt + (size_t)nxt.pn * tstep : cB;
;         for (int t = 0; t < nt; t += 2) {
;             const bool last = (t == nt - 2);
;             const char* a1 = cA + (size_t)(t + 1) * kstepA;
;             const char* a2 = last ? nA : cA + (size_t)(t + 2) * kstepA; const char* b2 = last ? nB : cB + (size_t)(t + 2) * kstep;
;             const char* a3 = a2 + kstepA; const char* b3 = b2 + kstep;
;             if (last && has_next) S.a_ready(nxt);
;             if constexpr (SP2) {
;             PG8_LDB(B0, 0, 0); PG8_LDB(B1, 0, 1); PG8_SCHED; PG8_LDA(At, 0, 0); PG8_STAGE(PG8_SA(1, 1), a1 + hstep, voffA);
;             PG8_WAIT_V(8); PG8_WAIT_L(0); PG8_BAR; PG8_MMA(0, 0, At, B0); PG8_MMA(0, 1, At, B1); PG8_BAR; PG8_SCHED;
;             PG8_LDA(At, 0, 1); PG8_STAGE(PG8_SB(0, 0), b2, voffB); PG8_STAGE(PG8_SB(0, 1), b2 + hstep, voffB); PG8_STAGE(PG8_SA(0, 0), a2, voffA);
.LBB0_408:
	s_ashr_i32 s11, s10, 31
	s_lshl_b64 s[12:13], s[10:11], 19
	s_add_u32 s12, s30, s12
	s_addc_u32 s13, s31, s13
	s_and_b64 s[18:19], s[4:5], exec
	s_cselect_b32 s11, s13, s23
	s_cselect_b32 s53, s12, s22
	s_ashr_i32 s9, s8, 31
	s_lshl_b64 s[18:19], s[8:9], 19
	s_add_u32 s18, s37, s18
	s_addc_u32 s19, s44, s19
	s_and_b64 s[26:27], s[4:5], exec
	s_cselect_b32 s9, s19, s25
	s_cselect_b32 s54, s18, s24
	s_add_u32 s55, s24, 0x100
	s_addc_u32 s56, s25, 0
	s_mov_b32 s57, -2
	s_add_u32 s24, s22, 0x8000
	s_addc_u32 s25, s23, 0
	s_cmp_eq_u32 s57, 12
	s_cselect_b32 s42, s53, s24
	s_cselect_b32 s43, s11, s25
	s_cselect_b32 s40, s54, s55
	s_cselect_b32 s41, s9, s56
	s_add_u32 s26, s42, 0x4000
	s_addc_u32 s27, s43, 0
	v_add_u32_e32 v145, s76, v142
	s_add_i32 s58, 0, 0x14000
	ds_read_b128 v[146:149], v145
	ds_read_b128 v[150:153], v145 offset:1024
	ds_read_b128 v[160:163], v145 offset:2048
	ds_read_b128 v[164:167], v145 offset:3072
	v_add_u32_e32 v145, s58, v142
	ds_read_b128 v[168:171], v145
	ds_read_b128 v[172:175], v145 offset:1024
	ds_read_b128 v[176:179], v145 offset:2048
	ds_read_b128 v[180:183], v145 offset:3072
	v_lshl_add_u64 v[230:231], s[22:23], 0, v[140:141]
	s_add_i32 m0, s45, 0xc000
	ds_read_b128 v[184:187], v144
	ds_read_b128 v[188:191], v144 offset:1024
	ds_read_b128 v[206:209], v144 offset:2048
	ds_read_b128 v[210:213], v144 offset:3072
	ds_read_b128 v[214:217], v144 offset:4096
	ds_read_b128 v[218:221], v144 offset:5120
	ds_read_b128 v[222:225], v144 offset:6144
	ds_read_b128 v[226:229], v144 offset:7168
	global_load_lds_dwordx4 v[230:231], off
	v_lshl_add_u64 v[230:231], s[22:23], 0, v[138:139]
	s_add_i32 m0, s45, 0xe000
	s_nop 0
	global_load_lds_dwordx4 v[230:231], off
	s_waitcnt vmcnt(8)
	s_waitcnt lgkmcnt(0)
	s_barrier
	v_mfma_f32_16x16x32_bf16 v[126:129], v[146:149], v[184:187], 0
	v_mfma_f32_16x16x32_bf16 v[126:129], v[150:153], v[188:191], v[126:129]
	v_mfma_f32_16x16x32_bf16 v[118:121], v[164:167], v[188:191], 0
	v_mfma_f32_16x16x32_bf16 v[118:121], v[160:163], v[184:187], v[118:121]
	v_mfma_f32_16x16x32_bf16 v[102:105], v[160:163], v[206:209], 0
	v_mfma_f32_16x16x32_bf16 v[102:105], v[164:167], v[210:213], v[102:105]
	v_mfma_f32_16x16x32_bf16 v[110:113], v[150:153], v[210:213], 0
	v_mfma_f32_16x16x32_bf16 v[110:113], v[146:149], v[206:209], v[110:113]
	v_mfma_f32_16x16x32_bf16 v[94:97], v[146:149], v[214:217], 0
	v_mfma_f32_16x16x32_bf16 v[94:97], v[150:153], v[218:221], v[94:97]
	v_mfma_f32_16x16x32_bf16 v[86:89], v[164:167], v[218:221], 0
	v_mfma_f32_16x16x32_bf16 v[86:89], v[160:163], v[214:217], v[86:89]
	v_mfma_f32_16x16x32_bf16 v[70:73], v[160:163], v[222:225], 0
	v_mfma_f32_16x16x32_bf16 v[70:73], v[164:167], v[226:229], v[70:73]
	v_mfma_f32_16x16x32_bf16 v[78:81], v[150:153], v[226:229], 0
	v_mfma_f32_16x16x32_bf16 v[78:81], v[146:149], v[222:225], v[78:81]
	v_mfma_f32_16x16x32_bf16 v[122:125], v[168:171], v[184:187], 0
	v_mfma_f32_16x16x32_bf16 v[122:125], v[172:175], v[188:191], v[122:125]
	v_mfma_f32_16x16x32_bf16 v[114:117], v[180:183], v[188:191], 0
	v_mfma_f32_16x16x32_bf16 v[114:117], v[176:179], v[184:187], v[114:117]
	v_mfma_f32_16x16x32_bf16 v[98:101], v[176:179], v[206:209], 0
	v_mfma_f32_16x16x32_bf16 v[98:101], v[180:183], v[210:213], v[98:101]
	v_mfma_f32_16x16x32_bf16 v[106:109], v[172:175], v[210:213], 0
	v_mfma_f32_16x16x32_bf16 v[106:109], v[168:171], v[206:209], v[106:109]
	v_mfma_f32_16x16x32_bf16 v[90:93], v[168:171], v[214:217], 0
	v_mfma_f32_16x16x32_bf16 v[90:93], v[172:175], v[218:221], v[90:93]
	v_mfma_f32_16x16x32_bf16 v[82:85], v[180:183], v[218:221], 0
	v_mfma_f32_16x16x32_bf16 v[82:85], v[176:179], v[214:217], v[82:85]
	v_mfma_f32_16x16x32_bf16 v[66:69], v[176:179], v[222:225], 0
	v_mfma_f32_16x16x32_bf16 v[66:69], v[180:183], v[226:229], v[66:69]
	v_mfma_f32_16x16x32_bf16 v[74:77], v[172:175], v[226:229], 0
	v_mfma_f32_16x16x32_bf16 v[74:77], v[168:171], v[222:225], v[74:77]
	s_barrier
	s_add_i32 s22, s76, s29
	v_lshl_add_u64 v[230:231], s[40:41], 0, v[0:1]
	s_mov_b32 m0, s22
	ds_read_b128 v[184:187], v144 offset:16384
	ds_read_b128 v[188:191], v144 offset:17408
	ds_read_b128 v[206:209], v144 offset:18432
	ds_read_b128 v[210:213], v144 offset:19456
	ds_read_b128 v[214:217], v144 offset:20480
	ds_read_b128 v[218:221], v144 offset:21504
	ds_read_b128 v[222:225], v144 offset:22528
	ds_read_b128 v[226:229], v144 offset:23552
	global_load_lds_dwordx4 v[230:231], off
	s_add_i32 m0, s22, 0x2000
	s_add_u32 s22, s40, 0x40000
	v_lshl_add_u64 v[232:233], s[40:41], 0, v[130:131]
	s_addc_u32 s23, s41, 0
	s_add_i32 s58, s58, s29
	global_load_lds_dwordx4 v[232:233], off
	v_lshl_add_u64 v[234:235], s[22:23], 0, v[0:1]
	s_mov_b32 m0, s58
	s_nop 0
	global_load_lds_dwordx4 v[234:235], off
	v_lshl_add_u64 v[234:235], s[22:23], 0, v[130:131]
	s_add_i32 m0, s58, 0x2000
	s_nop 0
	global_load_lds_dwordx4 v[234:235], off
	v_lshl_add_u64 v[234:235], s[42:43], 0, v[134:135]
	s_mov_b32 m0, s45
	s_nop 0
	global_load_lds_dwordx4 v[234:235], off
	v_lshl_add_u64 v[234:235], s[42:43], 0, v[132:133]
	s_mov_b32 m0, s46
	s_nop 0
	global_load_lds_dwordx4 v[234:235], off
	s_waitcnt vmcnt(8)
	s_waitcnt lgkmcnt(0)
	s_barrier
; #define PG8_STAGE(bufoff, gbase, voff) do { _Pragma("unroll") for (int _i = 0; _i < 2; ++_i) \
;         __builtin_amdgcn_global_load_lds((const unsigned*)((const char*)(gbase) + (voff)[_i]), (PG8_LAS unsigned*)(lds + (bufoff) + ldsw + _i * 8192), 16, 0, 0); } while (0)
; #define PG8_LDA(dst, b, h) do { _Pragma("unroll") for (int m = 0; m < 4; ++m) _Pragma("unroll") for (int k = 0; k < 2; ++k) dst[m][k] = *(const PG8_LAS bf16x8*)(lds + PG8_SA(b, h) + aoff + m * 2048 + k * 1024); } while (0)
; #define PG8_LDB(dst, b, h) do { _Pragma("unroll") for (int n = 0; n < 2; ++n) _Pragma("unroll") for (int k = 0; k < 2; ++k) dst[n][k] = *(const PG8_LAS bf16x8*)(lds + PG8_SB(b, h) + boff + n * 2048 + k * 1024); } while (0)
; #define PG8_MMA(ai, bj, At, Bt) do { __builtin_amdgcn_s_setprio(1); _Pragma("unroll") for (int m = 0; m < 4; ++m) _Pragma("unroll") for (int n = 0; n < 2; ++n) _Pragma("unroll") for (int k = 0; k < 2; ++k) \
;         acc[ai][bj][m][n] = __builtin_amdgcn_mfma_f32_16x16x32_bf16(Bt[n][k], At[m][k], acc[ai][bj][m][n], 0, 0, 0); __builtin_amdgcn_s_setprio(0); } while (0)
; #define PG8_WAIT_V(n) asm volatile("s_waitcnt vmcnt(" #n ")" ::: "memory")
; #define PG8_WAIT_L(n) asm volatile("s_waitcnt lgkmcnt(" #n ")" ::: "memory")
; #define PG8_BAR __builtin_amdgcn_s_barrier()
; #define PG8_SCHED __builtin_amdgcn_sched_barrier(0)
; template <class Epi, class Sched, bool ALIGN_EPI = false, bool SP2 = false>
; __device__ __forceinline__ void gemm_phase(PG8_LAS unsigned char* lds, const Gemm g, const Sched& S, const Epi& E) {
;     ...
;             PG8_WAIT_V(8); PG8_WAIT_L(0); PG8_BAR; PG8_MMA(1, 0, At, B0); PG8_MMA(1, 1, At, B1); PG8_BAR; PG8_SCHED;
;             PG8_LDB(B0, 1, 0); PG8_LDB(B1, 1, 1); PG8_SCHED; PG8_LDA(At, 1, 0); PG8_STAGE(PG8_SA(0, 1), a2 + hstep, voffA);
;             PG8_WAIT_V(8); PG8_WAIT_L(0); PG8_BAR; PG8_MMA(0, 0, At, B0); PG8_MMA(0, 1, At, B1); PG8_BAR; PG8_SCHED;
	v_mfma_f32_16x16x32_bf16 v[62:65], v[146:149], v[184:187], 0
	v_mfma_f32_16x16x32_bf16 v[62:65], v[150:153], v[188:191], v[62:65]
	v_mfma_f32_16x16x32_bf16 v[54:57], v[164:167], v[188:191], 0
	v_mfma_f32_16x16x32_bf16 v[54:57], v[160:163], v[184:187], v[54:57]
	v_mfma_f32_16x16x32_bf16 v[38:41], v[160:163], v[206:209], 0
	v_mfma_f32_16x16x32_bf16 v[38:41], v[164:167], v[210:213], v[38:41]
	v_mfma_f32_16x16x32_bf16 v[46:49], v[150:153], v[210:213], 0
	v_mfma_f32_16x16x32_bf16 v[46:49], v[146:149], v[206:209], v[46:49]
	v_mfma_f32_16x16x32_bf16 v[30:33], v[146:149], v[214:217], 0
	v_mfma_f32_16x16x32_bf16 v[30:33], v[150:153], v[218:221], v[30:33]
	v_mfma_f32_16x16x32_bf16 v[22:25], v[164:167], v[218:221], 0
	v_mfma_f32_16x16x32_bf16 v[22:25], v[160:163], v[214:217], v[22:25]
	v_mfma_f32_16x16x32_bf16 v[6:9], v[160:163], v[222:225], 0
	v_mfma_f32_16x16x32_bf16 v[6:9], v[164:167], v[226:229], v[6:9]
	v_mfma_f32_16x16x32_bf16 v[14:17], v[150:153], v[226:229], 0
	v_mfma_f32_16x16x32_bf16 v[14:17], v[146:149], v[222:225], v[14:17]
	v_mfma_f32_16x16x32_bf16 v[58:61], v[168:171], v[184:187], 0
	v_mfma_f32_16x16x32_bf16 v[58:61], v[172:175], v[188:191], v[58:61]
	v_mfma_f32_16x16x32_bf16 v[50:53], v[180:183], v[188:191], 0
	v_mfma_f32_16x16x32_bf16 v[50:53], v[176:179], v[184:187], v[50:53]
	v_mfma_f32_16x16x32_bf16 v[34:37], v[176:179], v[206:209], 0
	v_mfma_f32_16x16x32_bf16 v[34:37], v[180:183], v[210:213], v[34:37]
	v_mfma_f32_16x16x32_bf16 v[42:45], v[172:175], v[210:213], 0
	v_mfma_f32_16x16x32_bf16 v[42:45], v[168:171], v[206:209], v[42:45]
	v_mfma_f32_16x16x32_bf16 v[26:29], v[168:171], v[214:217], 0
	v_mfma_f32_16x16x32_bf16 v[26:29], v[172:175], v[218:221], v[26:29]
	v_mfma_f32_16x16x32_bf16 v[18:21], v[180:183], v[218:221], 0
	v_mfma_f32_16x16x32_bf16 v[18:21], v[176:179], v[214:217], v[18:21]
	v_mfma_f32_16x16x32_bf16 v[2:5], v[176:179], v[222:225], 0
	v_mfma_f32_16x16x32_bf16 v[2:5], v[180:183], v[226:229], v[2:5]
	v_mfma_f32_16x16x32_bf16 v[10:13], v[172:175], v[226:229], 0
	v_mfma_f32_16x16x32_bf16 v[10:13], v[168:171], v[222:225], v[10:13]
	s_barrier
	s_add_i32 s58, 0, 0x18000
	v_add_u32_e32 v145, s58, v142
	s_add_i32 s59, 0, 0x1c000
	ds_read_b128 v[146:149], v145
	ds_read_b128 v[150:153], v145 offset:1024
	ds_read_b128 v[160:163], v145 offset:2048
	ds_read_b128 v[164:167], v145 offset:3072
	v_add_u32_e32 v145, s59, v142
	ds_read_b128 v[168:171], v145
	ds_read_b128 v[172:175], v145 offset:1024
	ds_read_b128 v[176:179], v145 offset:2048
	ds_read_b128 v[180:183], v145 offset:3072
	s_add_u32 s22, s42, 0x40000
	s_addc_u32 s23, s43, 0
	s_mov_b32 m0, s47
	v_lshl_add_u64 v[234:235], s[22:23], 0, v[134:135]
	ds_read_b128 v[184:187], v144 offset:32768
	ds_read_b128 v[188:191], v144 offset:33792
	ds_read_b128 v[206:209], v144 offset:34816
	ds_read_b128 v[210:213], v144 offset:35840
	ds_read_b128 v[214:217], v144 offset:36864
	ds_read_b128 v[218:221], v144 offset:37888
	ds_read_b128 v[222:225], v144 offset:38912
	ds_read_b128 v[226:229], v144 offset:39936
	global_load_lds_dwordx4 v[234:235], off
	v_lshl_add_u64 v[234:235], s[22:23], 0, v[132:133]
	s_mov_b32 m0, s48
	s_nop 0
	global_load_lds_dwordx4 v[234:235], off
	s_waitcnt vmcnt(8)
	s_waitcnt lgkmcnt(0)
	s_barrier
	v_mfma_f32_16x16x32_bf16 v[126:129], v[146:149], v[184:187], v[126:129]
	v_mfma_f32_16x16x32_bf16 v[126:129], v[150:153], v[188:191], v[126:129]
	v_mfma_f32_16x16x32_bf16 v[118:121], v[164:167], v[188:191], v[118:121]
	v_mfma_f32_16x16x32_bf16 v[118:121], v[160:163], v[184:187], v[118:121]
	v_mfma_f32_16x16x32_bf16 v[102:105], v[160:163], v[206:209], v[102:105]
	v_mfma_f32_16x16x32_bf16 v[102:105], v[164:167], v[210:213], v[102:105]
	v_mfma_f32_16x16x32_bf16 v[110:113], v[150:153], v[210:213], v[110:113]
	v_mfma_f32_16x16x32_bf16 v[110:113], v[146:149], v[206:209], v[110:113]
	v_mfma_f32_16x16x32_bf16 v[94:97], v[146:149], v[214:217], v[94:97]
	v_mfma_f32_16x16x32_bf16 v[94:97], v[150:153], v[218:221], v[94:97]
	v_mfma_f32_16x16x32_bf16 v[86:89], v[164:167], v[218:221], v[86:89]
	v_mfma_f32_16x16x32_bf16 v[86:89], v[160:163], v[214:217], v[86:89]
	v_mfma_f32_16x16x32_bf16 v[70:73], v[160:163], v[222:225], v[70:73]
	v_mfma_f32_16x16x32_bf16 v[70:73], v[164:167], v[226:229], v[70:73]
	v_mfma_f32_16x16x32_bf16 v[78:81], v[150:153], v[226:229], v[78:81]
	v_mfma_f32_16x16x32_bf16 v[78:81], v[146:149], v[222:225], v[78:81]
	v_mfma_f32_16x16x32_bf16 v[122:125], v[168:171], v[184:187], v[122:125]
	v_mfma_f32_16x16x32_bf16 v[122:125], v[172:175], v[188:191], v[122:125]
	v_mfma_f32_16x16x32_bf16 v[114:117], v[180:183], v[188:191], v[114:117]
	v_mfma_f32_16x16x32_bf16 v[114:117], v[176:179], v[184:187], v[114:117]
	v_mfma_f32_16x16x32_bf16 v[98:101], v[176:179], v[206:209], v[98:101]
	v_mfma_f32_16x16x32_bf16 v[98:101], v[180:183], v[210:213], v[98:101]
	v_mfma_f32_16x16x32_bf16 v[106:109], v[172:175], v[210:213], v[106:109]
	v_mfma_f32_16x16x32_bf16 v[106:109], v[168:171], v[206:209], v[106:109]
	v_mfma_f32_16x16x32_bf16 v[90:93], v[168:171], v[214:217], v[90:93]
	v_mfma_f32_16x16x32_bf16 v[90:93], v[172:175], v[218:221], v[90:93]
	v_mfma_f32_16x16x32_bf16 v[82:85], v[180:183], v[218:221], v[82:85]
	v_mfma_f32_16x16x32_bf16 v[82:85], v[176:179], v[214:217], v[82:85]
	v_mfma_f32_16x16x32_bf16 v[66:69], v[176:179], v[222:225], v[66:69]
	v_mfma_f32_16x16x32_bf16 v[66:69], v[180:183], v[226:229], v[66:69]
	v_mfma_f32_16x16x32_bf16 v[74:77], v[172:175], v[226:229], v[74:77]
	v_mfma_f32_16x16x32_bf16 v[74:77], v[168:171], v[222:225], v[74:77]
	s_barrier
; #define PG8_STAGE(bufoff, gbase, voff) do { _Pragma("unroll") for (int _i = 0; _i < 2; ++_i) \
;         __builtin_amdgcn_global_load_lds((const unsigned*)((const char*)(gbase) + (voff)[_i]), (PG8_LAS unsigned*)(lds + (bufoff) + ldsw + _i * 8192), 16, 0, 0); } while (0)
; #define PG8_LDA(dst, b, h) do { _Pragma("unroll") for (int m = 0; m < 4; ++m) _Pragma("unroll") for (int k = 0; k < 2; ++k) dst[m][k] = *(const PG8_LAS bf16x8*)(lds + PG8_SA(b, h) + aoff + m * 2048 + k * 1024); } while (0)
; #define PG8_LDB(dst, b, h) do { _Pragma("unroll") for (int n = 0; n < 2; ++n) _Pragma("unroll") for (int k = 0; k < 2; ++k) dst[n][k] = *(const PG8_LAS bf16x8*)(lds + PG8_SB(b, h) + boff + n * 2048 + k * 1024); } while (0)
; #define PG8_MMA(ai, bj, At, Bt) do { __builtin_amdgcn_s_setprio(1); _Pragma("unroll") for (int m = 0; m < 4; ++m) _Pragma("unroll") for (int n = 0; n < 2; ++n) _Pragma("unroll") for (int k = 0; k < 2; ++k) \
;         acc[ai][bj][m][n] = __builtin_amdgcn_mfma_f32_16x16x32_bf16(Bt[n][k], At[m][k], acc[ai][bj][m][n], 0, 0, 0); __builtin_amdgcn_s_setprio(0); } while (0)
; #define PG8_WAIT_V(n) asm volatile("s_waitcnt vmcnt(" #n ")" ::: "memory")
; #define PG8_WAIT_L(n) asm volatile("s_waitcnt lgkmcnt(" #n ")" ::: "memory")
; #define PG8_BAR __builtin_amdgcn_s_barrier()
; #define PG8_SCHED __builtin_amdgcn_sched_barrier(0)
; template <class Epi, class Sched, bool ALIGN_EPI = false, bool SP2 = false>
; __device__ __forceinline__ void gemm_phase(PG8_LAS unsigned char* lds, const Gemm g, const Sched& S, const Epi& E) {
;     ...
;             PG8_LDB(B0, 0, 0); PG8_LDB(B1, 0, 1); PG8_SCHED; PG8_LDA(At, 0, 0); PG8_STAGE(PG8_SA(1, 1), a1 + hstep, voffA);
;             PG8_WAIT_V(8); PG8_WAIT_L(0); PG8_BAR; PG8_MMA(0, 0, At, B0); PG8_MMA(0, 1, At, B1); PG8_BAR; PG8_SCHED;
;     ...
;             PG8_LDA(At, 1, 1); PG8_STAGE(PG8_SB(1, 0), b3, voffB); PG8_STAGE(PG8_SB(1, 1), b3 + hstep, voffB); PG8_STAGE(PG8_SA(1, 0), a3, voffA);
;             PG8_WAIT_V(8); PG8_WAIT_L(0); PG8_BAR; PG8_MMA(1, 0, At, B0); PG8_MMA(1, 1, At, B1); PG8_BAR; PG8_SCHED;
	s_add_i32 s22, s58, s29
	v_lshl_add_u64 v[230:231], v[230:231], 0, s[38:39]
	s_mov_b32 m0, s22
	ds_read_b128 v[184:187], v144 offset:49152
	ds_read_b128 v[188:191], v144 offset:50176
	ds_read_b128 v[206:209], v144 offset:51200
	ds_read_b128 v[210:213], v144 offset:52224
	ds_read_b128 v[214:217], v144 offset:53248
	ds_read_b128 v[218:221], v144 offset:54272
	ds_read_b128 v[222:225], v144 offset:55296
	ds_read_b128 v[226:229], v144 offset:56320
	global_load_lds_dwordx4 v[230:231], off
	s_add_i32 m0, s22, 0x2000
	s_add_u32 s22, s40, 0x40080
	v_lshl_add_u64 v[230:231], v[232:233], 0, s[38:39]
	s_addc_u32 s23, s41, 0
	s_add_i32 s40, s59, s29
	global_load_lds_dwordx4 v[230:231], off
	v_lshl_add_u64 v[230:231], s[22:23], 0, v[0:1]
	s_mov_b32 m0, s40
	s_nop 0
	global_load_lds_dwordx4 v[230:231], off
	v_lshl_add_u64 v[230:231], s[22:23], 0, v[130:131]
	s_add_i32 m0, s40, 0x2000
	s_nop 0
	global_load_lds_dwordx4 v[230:231], off
	v_lshl_add_u64 v[230:231], s[26:27], 0, v[134:135]
	s_mov_b32 m0, s49
	s_nop 0
	global_load_lds_dwordx4 v[230:231], off
	v_lshl_add_u64 v[230:231], s[26:27], 0, v[132:133]
	s_mov_b32 m0, s50
	s_nop 0
	global_load_lds_dwordx4 v[230:231], off
	s_waitcnt vmcnt(8)
	s_waitcnt lgkmcnt(0)
	s_barrier
	v_mfma_f32_16x16x32_bf16 v[62:65], v[146:149], v[184:187], v[62:65]
	v_mfma_f32_16x16x32_bf16 v[62:65], v[150:153], v[188:191], v[62:65]
	v_mfma_f32_16x16x32_bf16 v[54:57], v[164:167], v[188:191], v[54:57]
	v_mfma_f32_16x16x32_bf16 v[54:57], v[160:163], v[184:187], v[54:57]
	v_mfma_f32_16x16x32_bf16 v[38:41], v[160:163], v[206:209], v[38:41]
	v_mfma_f32_16x16x32_bf16 v[38:41], v[164:167], v[210:213], v[38:41]
	v_mfma_f32_16x16x32_bf16 v[46:49], v[150:153], v[210:213], v[46:49]
	v_mfma_f32_16x16x32_bf16 v[46:49], v[146:149], v[206:209], v[46:49]
	v_mfma_f32_16x16x32_bf16 v[30:33], v[146:149], v[214:217], v[30:33]
	v_mfma_f32_16x16x32_bf16 v[30:33], v[150:153], v[218:221], v[30:33]
	v_mfma_f32_16x16x32_bf16 v[22:25], v[164:167], v[218:221], v[22:25]
	v_mfma_f32_16x16x32_bf16 v[22:25], v[160:163], v[214:217], v[22:25]
	v_mfma_f32_16x16x32_bf16 v[6:9], v[160:163], v[222:225], v[6:9]
	v_mfma_f32_16x16x32_bf16 v[6:9], v[164:167], v[226:229], v[6:9]
	v_mfma_f32_16x16x32_bf16 v[14:17], v[150:153], v[226:229], v[14:17]
	v_mfma_f32_16x16x32_bf16 v[14:17], v[146:149], v[222:225], v[14:17]
	v_mfma_f32_16x16x32_bf16 v[58:61], v[168:171], v[184:187], v[58:61]
	v_mfma_f32_16x16x32_bf16 v[58:61], v[172:175], v[188:191], v[58:61]
	v_mfma_f32_16x16x32_bf16 v[50:53], v[180:183], v[188:191], v[50:53]
	v_mfma_f32_16x16x32_bf16 v[50:53], v[176:179], v[184:187], v[50:53]
	v_mfma_f32_16x16x32_bf16 v[34:37], v[176:179], v[206:209], v[34:37]
	v_mfma_f32_16x16x32_bf16 v[34:37], v[180:183], v[210:213], v[34:37]
	v_mfma_f32_16x16x32_bf16 v[42:45], v[172:175], v[210:213], v[42:45]
	v_mfma_f32_16x16x32_bf16 v[42:45], v[168:171], v[206:209], v[42:45]
	v_mfma_f32_16x16x32_bf16 v[26:29], v[168:171], v[214:217], v[26:29]
	v_mfma_f32_16x16x32_bf16 v[26:29], v[172:175], v[218:221], v[26:29]
	v_mfma_f32_16x16x32_bf16 v[18:21], v[180:183], v[218:221], v[18:21]
	v_mfma_f32_16x16x32_bf16 v[18:21], v[176:179], v[214:217], v[18:21]
	v_mfma_f32_16x16x32_bf16 v[2:5], v[176:179], v[222:225], v[2:5]
	v_mfma_f32_16x16x32_bf16 v[2:5], v[180:183], v[226:229], v[2:5]
	v_mfma_f32_16x16x32_bf16 v[10:13], v[172:175], v[226:229], v[10:13]
	v_mfma_f32_16x16x32_bf16 v[10:13], v[168:171], v[222:225], v[10:13]
	s_barrier
	s_add_i32 s57, s57, 2
	s_add_u32 s55, s55, 0x100
	s_addc_u32 s56, s56, 0
	s_cmp_gt_u32 s57, 13
	s_mov_b64 s[22:23], s[24:25]
	s_cbranch_scc1 .Lpeel_exit_2
.LBB0_409:
	s_add_u32 s24, s22, 0x8000
	s_addc_u32 s25, s23, 0
	s_cmp_eq_u32 s57, 12
	s_cselect_b32 s42, s53, s24
	s_cselect_b32 s43, s11, s25
	s_cselect_b32 s40, s54, s55
	s_cselect_b32 s41, s9, s56
	s_add_u32 s26, s42, 0x4000
	s_addc_u32 s27, s43, 0
	v_add_u32_e32 v145, s76, v142
	s_add_i32 s58, 0, 0x14000
	ds_read_b128 v[146:149], v145
	ds_read_b128 v[150:153], v145 offset:1024
	ds_read_b128 v[160:163], v145 offset:2048
	ds_read_b128 v[164:167], v145 offset:3072
	v_add_u32_e32 v145, s58, v142
	ds_read_b128 v[168:171], v145
	ds_read_b128 v[172:175], v145 offset:1024
	ds_read_b128 v[176:179], v145 offset:2048
	ds_read_b128 v[180:183], v145 offset:3072
	v_lshl_add_u64 v[230:231], s[22:23], 0, v[140:141]
	s_add_i32 m0, s45, 0xc000
	ds_read_b128 v[184:187], v144
	ds_read_b128 v[188:191], v144 offset:1024
	ds_read_b128 v[206:209], v144 offset:2048
	ds_read_b128 v[210:213], v144 offset:3072
	ds_read_b128 v[214:217], v144 offset:4096
	ds_read_b128 v[218:221], v144 offset:5120
	ds_read_b128 v[222:225], v144 offset:6144
	ds_read_b128 v[226:229], v144 offset:7168
	global_load_lds_dwordx4 v[230:231], off
	v_lshl_add_u64 v[230:231], s[22:23], 0, v[138:139]
	s_add_i32 m0, s45, 0xe000
	s_nop 0
	global_load_lds_dwordx4 v[230:231], off
	s_waitcnt vmcnt(8)
	s_waitcnt lgkmcnt(0)
	s_barrier
; #define PG8_STAGE(bufoff, gbase, voff) do { _Pragma("unroll") for (int _i = 0; _i < 2; ++_i) \
;         __builtin_amdgcn_global_load_lds((const unsigned*)((const char*)(gbase) + (voff)[_i]), (PG8_LAS unsigned*)(lds + (bufoff) + ldsw + _i * 8192), 16, 0, 0); } while (0)
; #define PG8_LDA(dst, b, h) do { _Pragma("unroll") for (int m = 0; m < 4; ++m) _Pragma("unroll") for (int k = 0; k < 2; ++k) dst[m][k] = *(const PG8_LAS bf16x8*)(lds + PG8_SA(b, h) + aoff + m * 2048 + k * 1024); } while (0)
; #define PG8_MMA(ai, bj, At, Bt) do { __builtin_amdgcn_s_setprio(1); _Pragma("unroll") for (int m = 0; m < 4; ++m) _Pragma("unroll") for (int n = 0; n < 2; ++n) _Pragma("unroll") for (int k = 0; k < 2; ++k) \
;         acc[ai][bj][m][n] = __builtin_amdgcn_mfma_f32_16x16x32_bf16(Bt[n][k], At[m][k], acc[ai][bj][m][n], 0, 0, 0); __builtin_amdgcn_s_setprio(0); } while (0)
; #define PG8_WAIT_V(n) asm volatile("s_waitcnt vmcnt(" #n ")" ::: "memory")
; #define PG8_WAIT_L(n) asm volatile("s_waitcnt lgkmcnt(" #n ")" ::: "memory")
; #define PG8_BAR __builtin_amdgcn_s_barrier()
; #define PG8_SCHED __builtin_amdgcn_sched_barrier(0)
; template <class Epi, class Sched, bool ALIGN_EPI = false, bool SP2 = false>
; __device__ __forceinline__ void gemm_phase(PG8_LAS unsigned char* lds, const Gemm g, const Sched& S, const Epi& E) {
;     ...
;             PG8_WAIT_V(8); PG8_WAIT_L(0); PG8_BAR; PG8_MMA(0, 0, At, B0); PG8_MMA(0, 1, At, B1); PG8_BAR; PG8_SCHED;
;             PG8_LDA(At, 0, 1); PG8_STAGE(PG8_SB(0, 0), b2, voffB); PG8_STAGE(PG8_SB(0, 1), b2 + hstep, voffB); PG8_STAGE(PG8_SA(0, 0), a2, voffA);
;             PG8_WAIT_V(8); PG8_WAIT_L(0); PG8_BAR; PG8_MMA(1, 0, At, B0); PG8_MMA(1, 1, At, B1); PG8_BAR; PG8_SCHED;
	v_mfma_f32_16x16x32_bf16 v[126:129], v[146:149], v[184:187], v[126:129]
	v_mfma_f32_16x16x32_bf16 v[126:129], v[150:153], v[188:191], v[126:129]
	v_mfma_f32_16x16x32_bf16 v[118:121], v[164:167], v[188:191], v[118:121]
	v_mfma_f32_16x16x32_bf16 v[118:121], v[160:163], v[184:187], v[118:121]
	v_mfma_f32_16x16x32_bf16 v[102:105], v[160:163], v[206:209], v[102:105]
	v_mfma_f32_16x16x32_bf16 v[102:105], v[164:167], v[210:213], v[102:105]
	v_mfma_f32_16x16x32_bf16 v[110:113], v[150:153], v[210:213], v[110:113]
	v_mfma_f32_16x16x32_bf16 v[110:113], v[146:149], v[206:209], v[110:113]
	v_mfma_f32_16x16x32_bf16 v[94:97], v[146:149], v[214:217], v[94:97]
	v_mfma_f32_16x16x32_bf16 v[94:97], v[150:153], v[218:221], v[94:97]
	v_mfma_f32_16x16x32_bf16 v[86:89], v[164:167], v[218:221], v[86:89]
	v_mfma_f32_16x16x32_bf16 v[86:89], v[160:163], v[214:217], v[86:89]
	v_mfma_f32_16x16x32_bf16 v[70:73], v[160:163], v[222:225], v[70:73]
	v_mfma_f32_16x16x32_bf16 v[70:73], v[164:167], v[226:229], v[70:73]
	v_mfma_f32_16x16x32_bf16 v[78:81], v[150:153], v[226:229], v[78:81]
	v_mfma_f32_16x16x32_bf16 v[78:81], v[146:149], v[222:225], v[78:81]
	v_mfma_f32_16x16x32_bf16 v[122:125], v[168:171], v[184:187], v[122:125]
	v_mfma_f32_16x16x32_bf16 v[122:125], v[172:175], v[188:191], v[122:125]
	v_mfma_f32_16x16x32_bf16 v[114:117], v[180:183], v[188:191], v[114:117]
	v_mfma_f32_16x16x32_bf16 v[114:117], v[176:179], v[184:187], v[114:117]
	v_mfma_f32_16x16x32_bf16 v[98:101], v[176:179], v[206:209], v[98:101]
	v_mfma_f32_16x16x32_bf16 v[98:101], v[180:183], v[210:213], v[98:101]
	v_mfma_f32_16x16x32_bf16 v[106:109], v[172:175], v[210:213], v[106:109]
	v_mfma_f32_16x16x32_bf16 v[106:109], v[168:171], v[206:209], v[106:109]
	v_mfma_f32_16x16x32_bf16 v[90:93], v[168:171], v[214:217], v[90:93]
	v_mfma_f32_16x16x32_bf16 v[90:93], v[172:175], v[218:221], v[90:93]
	v_mfma_f32_16x16x32_bf16 v[82:85], v[180:183], v[218:221], v[82:85]
	v_mfma_f32_16x16x32_bf16 v[82:85], v[176:179], v[214:217], v[82:85]
	v_mfma_f32_16x16x32_bf16 v[66:69], v[176:179], v[222:225], v[66:69]
	v_mfma_f32_16x16x32_bf16 v[66:69], v[180:183], v[226:229], v[66:69]
	v_mfma_f32_16x16x32_bf16 v[74:77], v[172:175], v[226:229], v[74:77]
	v_mfma_f32_16x16x32_bf16 v[74:77], v[168:171], v[222:225], v[74:77]
	s_barrier
	s_add_i32 s22, s76, s29
	v_lshl_add_u64 v[230:231], s[40:41], 0, v[0:1]
	s_mov_b32 m0, s22
	ds_read_b128 v[184:187], v144 offset:16384
	ds_read_b128 v[188:191], v144 offset:17408
	ds_read_b128 v[206:209], v144 offset:18432
	ds_read_b128 v[210:213], v144 offset:19456
	ds_read_b128 v[214:217], v144 offset:20480
	ds_read_b128 v[218:221], v144 offset:21504
	ds_read_b128 v[222:225], v144 offset:22528
	ds_read_b128 v[226:229], v144 offset:23552
	global_load_lds_dwordx4 v[230:231], off
	s_add_i32 m0, s22, 0x2000
	s_add_u32 s22, s40, 0x40000
	v_lshl_add_u64 v[232:233], s[40:41], 0, v[130:131]
	s_addc_u32 s23, s41, 0
	s_add_i32 s58, s58, s29
	global_load_lds_dwordx4 v[232:233], off
	v_lshl_add_u64 v[234:235], s[22:23], 0, v[0:1]
	s_mov_b32 m0, s58
	s_nop 0
	global_load_lds_dwordx4 v[234:235], off
	v_lshl_add_u64 v[234:235], s[22:23], 0, v[130:131]
	s_add_i32 m0, s58, 0x2000
	s_nop 0
	global_load_lds_dwordx4 v[234:235], off
	v_lshl_add_u64 v[234:235], s[42:43], 0, v[134:135]
	s_mov_b32 m0, s45
	s_nop 0
	global_load_lds_dwordx4 v[234:235], off
	v_lshl_add_u64 v[234:235], s[42:43], 0, v[132:133]
	s_mov_b32 m0, s46
	s_nop 0
	global_load_lds_dwordx4 v[234:235], off
	s_waitcnt vmcnt(8)
	s_waitcnt lgkmcnt(0)
	s_barrier
	v_mfma_f32_16x16x32_bf16 v[62:65], v[146:149], v[184:187], v[62:65]
	v_mfma_f32_16x16x32_bf16 v[62:65], v[150:153], v[188:191], v[62:65]
	v_mfma_f32_16x16x32_bf16 v[54:57], v[164:167], v[188:191], v[54:57]
	v_mfma_f32_16x16x32_bf16 v[54:57], v[160:163], v[184:187], v[54:57]
	v_mfma_f32_16x16x32_bf16 v[38:41], v[160:163], v[206:209], v[38:41]
	v_mfma_f32_16x16x32_bf16 v[38:41], v[164:167], v[210:213], v[38:41]
	v_mfma_f32_16x16x32_bf16 v[46:49], v[150:153], v[210:213], v[46:49]
	v_mfma_f32_16x16x32_bf16 v[46:49], v[146:149], v[206:209], v[46:49]
	v_mfma_f32_16x16x32_bf16 v[30:33], v[146:149], v[214:217], v[30:33]
	v_mfma_f32_16x16x32_bf16 v[30:33], v[150:153], v[218:221], v[30:33]
	v_mfma_f32_16x16x32_bf16 v[22:25], v[164:167], v[218:221], v[22:25]
	v_mfma_f32_16x16x32_bf16 v[22:25], v[160:163], v[214:217], v[22:25]
	v_mfma_f32_16x16x32_bf16 v[6:9], v[160:163], v[222:225], v[6:9]
	v_mfma_f32_16x16x32_bf16 v[6:9], v[164:167], v[226:229], v[6:9]
	v_mfma_f32_16x16x32_bf16 v[14:17], v[150:153], v[226:229], v[14:17]
	v_mfma_f32_16x16x32_bf16 v[14:17], v[146:149], v[222:225], v[14:17]
	v_mfma_f32_16x16x32_bf16 v[58:61], v[168:171], v[184:187], v[58:61]
	v_mfma_f32_16x16x32_bf16 v[58:61], v[172:175], v[188:191], v[58:61]
	v_mfma_f32_16x16x32_bf16 v[50:53], v[180:183], v[188:191], v[50:53]
	v_mfma_f32_16x16x32_bf16 v[50:53], v[176:179], v[184:187], v[50:53]
	v_mfma_f32_16x16x32_bf16 v[34:37], v[176:179], v[206:209], v[34:37]
	v_mfma_f32_16x16x32_bf16 v[34:37], v[180:183], v[210:213], v[34:37]
	v_mfma_f32_16x16x32_bf16 v[42:45], v[172:175], v[210:213], v[42:45]
	v_mfma_f32_16x16x32_bf16 v[42:45], v[168:171], v[206:209], v[42:45]
	v_mfma_f32_16x16x32_bf16 v[26:29], v[168:171], v[214:217], v[26:29]
	v_mfma_f32_16x16x32_bf16 v[26:29], v[172:175], v[218:221], v[26:29]
	v_mfma_f32_16x16x32_bf16 v[18:21], v[180:183], v[218:221], v[18:21]
	v_mfma_f32_16x16x32_bf16 v[18:21], v[176:179], v[214:217], v[18:21]
	v_mfma_f32_16x16x32_bf16 v[2:5], v[176:179], v[222:225], v[2:5]
	v_mfma_f32_16x16x32_bf16 v[2:5], v[180:183], v[226:229], v[2:5]
	v_mfma_f32_16x16x32_bf16 v[10:13], v[172:175], v[226:229], v[10:13]
	v_mfma_f32_16x16x32_bf16 v[10:13], v[168:171], v[222:225], v[10:13]
	s_barrier
; #define PG8_STAGE(bufoff, gbase, voff) do { _Pragma("unroll") for (int _i = 0; _i < 2; ++_i) \
;         __builtin_amdgcn_global_load_lds((const unsigned*)((const char*)(gbase) + (voff)[_i]), (PG8_LAS unsigned*)(lds + (bufoff) + ldsw + _i * 8192), 16, 0, 0); } while (0)
; #define PG8_LDA(dst, b, h) do { _Pragma("unroll") for (int m = 0; m < 4; ++m) _Pragma("unroll") for (int k = 0; k < 2; ++k) dst[m][k] = *(const PG8_LAS bf16x8*)(lds + PG8_SA(b, h) + aoff + m * 2048 + k * 1024); } while (0)
; #define PG8_LDB(dst, b, h) do { _Pragma("unroll") for (int n = 0; n < 2; ++n) _Pragma("unroll") for (int k = 0; k < 2; ++k) dst[n][k] = *(const PG8_LAS bf16x8*)(lds + PG8_SB(b, h) + boff + n * 2048 + k * 1024); } while (0)
; #define PG8_MMA(ai, bj, At, Bt) do { __builtin_amdgcn_s_setprio(1); _Pragma("unroll") for (int m = 0; m < 4; ++m) _Pragma("unroll") for (int n = 0; n < 2; ++n) _Pragma("unroll") for (int k = 0; k < 2; ++k) \
;         acc[ai][bj][m][n] = __builtin_amdgcn_mfma_f32_16x16x32_bf16(Bt[n][k], At[m][k], acc[ai][bj][m][n], 0, 0, 0); __builtin_amdgcn_s_setprio(0); } while (0)
; #define PG8_WAIT_V(n) asm volatile("s_waitcnt vmcnt(" #n ")" ::: "memory")
; #define PG8_WAIT_L(n) asm volatile("s_waitcnt lgkmcnt(" #n ")" ::: "memory")
; #define PG8_BAR __builtin_amdgcn_s_barrier()
; #define PG8_SCHED __builtin_amdgcn_sched_barrier(0)
; template <class Epi, class Sched, bool ALIGN_EPI = false, bool SP2 = false>
; __device__ __forceinline__ void gemm_phase(PG8_LAS unsigned char* lds, const Gemm g, const Sched& S, const Epi& E) {
;     ...
;             PG8_LDB(B0, 1, 0); PG8_LDB(B1, 1, 1); PG8_SCHED; PG8_LDA(At, 1, 0); PG8_STAGE(PG8_SA(0, 1), a2 + hstep, voffA);
;             PG8_WAIT_V(8); PG8_WAIT_L(0); PG8_BAR; PG8_MMA(0, 0, At, B0); PG8_MMA(0, 1, At, B1); PG8_BAR; PG8_SCHED;
;             PG8_LDA(At, 1, 1); PG8_STAGE(PG8_SB(1, 0), b3, voffB); PG8_STAGE(PG8_SB(1, 1), b3 + hstep, voffB); PG8_STAGE(PG8_SA(1, 0), a3, voffA);
;             PG8_WAIT_V(8); PG8_WAIT_L(0); PG8_BAR; PG8_MMA(1, 0, At, B0); PG8_MMA(1, 1, At, B1); PG8_BAR; PG8_SCHED;
	s_add_i32 s58, 0, 0x18000
	v_add_u32_e32 v145, s58, v142
	s_add_i32 s59, 0, 0x1c000
	ds_read_b128 v[146:149], v145
	ds_read_b128 v[150:153], v145 offset:1024
	ds_read_b128 v[160:163], v145 offset:2048
	ds_read_b128 v[164:167], v145 offset:3072
	v_add_u32_e32 v145, s59, v142
	ds_read_b128 v[168:171], v145
	ds_read_b128 v[172:175], v145 offset:1024
	ds_read_b128 v[176:179], v145 offset:2048
	ds_read_b128 v[180:183], v145 offset:3072
	s_add_u32 s22, s42, 0x40000
	s_addc_u32 s23, s43, 0
	s_mov_b32 m0, s47
	v_lshl_add_u64 v[234:235], s[22:23], 0, v[134:135]
	ds_read_b128 v[184:187], v144 offset:32768
	ds_read_b128 v[188:191], v144 offset:33792
	ds_read_b128 v[206:209], v144 offset:34816
	ds_read_b128 v[210:213], v144 offset:35840
	ds_read_b128 v[214:217], v144 offset:36864
	ds_read_b128 v[218:221], v144 offset:37888
	ds_read_b128 v[222:225], v144 offset:38912
	ds_read_b128 v[226:229], v144 offset:39936
	global_load_lds_dwordx4 v[234:235], off
	v_lshl_add_u64 v[234:235], s[22:23], 0, v[132:133]
	s_mov_b32 m0, s48
	s_nop 0
	global_load_lds_dwordx4 v[234:235], off
	s_waitcnt vmcnt(8)
	s_waitcnt lgkmcnt(0)
	s_barrier
	v_mfma_f32_16x16x32_bf16 v[126:129], v[146:149], v[184:187], v[126:129]
	v_mfma_f32_16x16x32_bf16 v[126:129], v[150:153], v[188:191], v[126:129]
	v_mfma_f32_16x16x32_bf16 v[118:121], v[164:167], v[188:191], v[118:121]
	v_mfma_f32_16x16x32_bf16 v[118:121], v[160:163], v[184:187], v[118:121]
	v_mfma_f32_16x16x32_bf16 v[102:105], v[160:163], v[206:209], v[102:105]
	v_mfma_f32_16x16x32_bf16 v[102:105], v[164:167], v[210:213], v[102:105]
	v_mfma_f32_16x16x32_bf16 v[110:113], v[150:153], v[210:213], v[110:113]
	v_mfma_f32_16x16x32_bf16 v[110:113], v[146:149], v[206:209], v[110:113]
	v_mfma_f32_16x16x32_bf16 v[94:97], v[146:149], v[214:217], v[94:97]
	v_mfma_f32_16x16x32_bf16 v[94:97], v[150:153], v[218:221], v[94:97]
	v_mfma_f32_16x16x32_bf16 v[86:89], v[164:167], v[218:221], v[86:89]
	v_mfma_f32_16x16x32_bf16 v[86:89], v[160:163], v[214:217], v[86:89]
	v_mfma_f32_16x16x32_bf16 v[70:73], v[160:163], v[222:225], v[70:73]
	v_mfma_f32_16x16x32_bf16 v[70:73], v[164:167], v[226:229], v[70:73]
	v_mfma_f32_16x16x32_bf16 v[78:81], v[150:153], v[226:229], v[78:81]
	v_mfma_f32_16x16x32_bf16 v[78:81], v[146:149], v[222:225], v[78:81]
	v_mfma_f32_16x16x32_bf16 v[122:125], v[168:171], v[184:187], v[122:125]
	v_mfma_f32_16x16x32_bf16 v[122:125], v[172:175], v[188:191], v[122:125]
	v_mfma_f32_16x16x32_bf16 v[114:117], v[180:183], v[188:191], v[114:117]
	v_mfma_f32_16x16x32_bf16 v[114:117], v[176:179], v[184:187], v[114:117]
	v_mfma_f32_16x16x32_bf16 v[98:101], v[176:179], v[206:209], v[98:101]
	v_mfma_f32_16x16x32_bf16 v[98:101], v[180:183], v[210:213], v[98:101]
	v_mfma_f32_16x16x32_bf16 v[106:109], v[172:175], v[210:213], v[106:109]
	v_mfma_f32_16x16x32_bf16 v[106:109], v[168:171], v[206:209], v[106:109]
	v_mfma_f32_16x16x32_bf16 v[90:93], v[168:171], v[214:217], v[90:93]
	v_mfma_f32_16x16x32_bf16 v[90:93], v[172:175], v[218:221], v[90:93]
	v_mfma_f32_16x16x32_bf16 v[82:85], v[180:183], v[218:221], v[82:85]
	v_mfma_f32_16x16x32_bf16 v[82:85], v[176:179], v[214:217], v[82:85]
	v_mfma_f32_16x16x32_bf16 v[66:69], v[176:179], v[222:225], v[66:69]
	v_mfma_f32_16x16x32_bf16 v[66:69], v[180:183], v[226:229], v[66:69]
	v_mfma_f32_16x16x32_bf16 v[74:77], v[172:175], v[226:229], v[74:77]
	v_mfma_f32_16x16x32_bf16 v[74:77], v[168:171], v[222:225], v[74:77]
	s_barrier
	s_add_i32 s22, s58, s29
	v_lshl_add_u64 v[230:231], v[230:231], 0, s[38:39]
	s_mov_b32 m0, s22
	ds_read_b128 v[184:187], v144 offset:49152
	ds_read_b128 v[188:191], v144 offset:50176
	ds_read_b128 v[206:209], v144 offset:51200
	ds_read_b128 v[210:213], v144 offset:52224
	ds_read_b128 v[214:217], v144 offset:53248
	ds_read_b128 v[218:221], v144 offset:54272
	ds_read_b128 v[222:225], v144 offset:55296
	ds_read_b128 v[226:229], v144 offset:56320
	global_load_lds_dwordx4 v[230:231], off
	s_add_i32 m0, s22, 0x2000
	s_add_u32 s22, s40, 0x40080
	v_lshl_add_u64 v[230:231], v[232:233], 0, s[38:39]
	s_addc_u32 s23, s41, 0
	s_add_i32 s40, s59, s29
	global_load_lds_dwordx4 v[230:231], off
	v_lshl_add_u64 v[230:231], s[22:23], 0, v[0:1]
	s_mov_b32 m0, s40
	s_nop 0
	global_load_lds_dwordx4 v[230:231], off
	v_lshl_add_u64 v[230:231], s[22:23], 0, v[130:131]
	s_add_i32 m0, s40, 0x2000
	s_nop 0
	global_load_lds_dwordx4 v[230:231], off
	v_lshl_add_u64 v[230:231], s[26:27], 0, v[134:135]
	s_mov_b32 m0, s49
	s_nop 0
	global_load_lds_dwordx4 v[230:231], off
	v_lshl_add_u64 v[230:231], s[26:27], 0, v[132:133]
	s_mov_b32 m0, s50
	s_nop 0
	global_load_lds_dwordx4 v[230:231], off
	s_waitcnt vmcnt(8)
	s_waitcnt lgkmcnt(0)
	s_barrier
	v_mfma_f32_16x16x32_bf16 v[62:65], v[146:149], v[184:187], v[62:65]
	v_mfma_f32_16x16x32_bf16 v[62:65], v[150:153], v[188:191], v[62:65]
	v_mfma_f32_16x16x32_bf16 v[54:57], v[164:167], v[188:191], v[54:57]
	v_mfma_f32_16x16x32_bf16 v[54:57], v[160:163], v[184:187], v[54:57]
	v_mfma_f32_16x16x32_bf16 v[38:41], v[160:163], v[206:209], v[38:41]
	v_mfma_f32_16x16x32_bf16 v[38:41], v[164:167], v[210:213], v[38:41]
	v_mfma_f32_16x16x32_bf16 v[46:49], v[150:153], v[210:213], v[46:49]
	v_mfma_f32_16x16x32_bf16 v[46:49], v[146:149], v[206:209], v[46:49]
	v_mfma_f32_16x16x32_bf16 v[30:33], v[146:149], v[214:217], v[30:33]
	v_mfma_f32_16x16x32_bf16 v[30:33], v[150:153], v[218:221], v[30:33]
	v_mfma_f32_16x16x32_bf16 v[22:25], v[164:167], v[218:221], v[22:25]
	v_mfma_f32_16x16x32_bf16 v[22:25], v[160:163], v[214:217], v[22:25]
	v_mfma_f32_16x16x32_bf16 v[6:9], v[160:163], v[222:225], v[6:9]
	v_mfma_f32_16x16x32_bf16 v[6:9], v[164:167], v[226:229], v[6:9]
	v_mfma_f32_16x16x32_bf16 v[14:17], v[150:153], v[226:229], v[14:17]
	v_mfma_f32_16x16x32_bf16 v[14:17], v[146:149], v[222:225], v[14:17]
	v_mfma_f32_16x16x32_bf16 v[58:61], v[168:171], v[184:187], v[58:61]
	v_mfma_f32_16x16x32_bf16 v[58:61], v[172:175], v[188:191], v[58:61]
	v_mfma_f32_16x16x32_bf16 v[50:53], v[180:183], v[188:191], v[50:53]
	v_mfma_f32_16x16x32_bf16 v[50:53], v[176:179], v[184:187], v[50:53]
	v_mfma_f32_16x16x32_bf16 v[34:37], v[176:179], v[206:209], v[34:37]
	v_mfma_f32_16x16x32_bf16 v[34:37], v[180:183], v[210:213], v[34:37]
	v_mfma_f32_16x16x32_bf16 v[42:45], v[172:175], v[210:213], v[42:45]
	v_mfma_f32_16x16x32_bf16 v[42:45], v[168:171], v[206:209], v[42:45]
	v_mfma_f32_16x16x32_bf16 v[26:29], v[168:171], v[214:217], v[26:29]
	v_mfma_f32_16x16x32_bf16 v[26:29], v[172:175], v[218:221], v[26:29]
	v_mfma_f32_16x16x32_bf16 v[18:21], v[180:183], v[218:221], v[18:21]
	v_mfma_f32_16x16x32_bf16 v[18:21], v[176:179], v[214:217], v[18:21]
	v_mfma_f32_16x16x32_bf16 v[2:5], v[176:179], v[222:225], v[2:5]
	v_mfma_f32_16x16x32_bf16 v[2:5], v[180:183], v[226:229], v[2:5]
	v_mfma_f32_16x16x32_bf16 v[10:13], v[172:175], v[226:229], v[10:13]
	v_mfma_f32_16x16x32_bf16 v[10:13], v[168:171], v[222:225], v[10:13]
	s_barrier
	s_add_i32 s57, s57, 2
	s_add_u32 s55, s55, 0x100
	s_addc_u32 s56, s56, 0
	s_cmp_gt_u32 s57, 13
	s_mov_b64 s[22:23], s[24:25]
	s_cbranch_scc0 .LBB0_409
